# gla3 tile head: second q/k/bcum batch and v loads issued with the first batch; gla1 head-loop wait counts stores on the back edge
# speedup vs baseline: 1.0025x; 1.0025x over previous
; __device__ __forceinline__ void gla_zl_chunk(const bf16* XN, const bf16* WzlT  , LAS unsigned char* lds, int c, int tid_in) {
;     ...
;     const bf16* ap = XN + (size_t)(c * CH + fr) * D + 256 * wave + fq * 8;
;     const bf16* bp = WzlT + (size_t)fr * D + 256 * wave + fq * 8;
; #pragma unroll
;     for (int ks = 0; ks < 8; ++ks) {
;         const bf16x8 b = *(const bf16x8*)(bp + ks * 32);
; #pragma unroll
;         for (int mt = 0; mt < 4; ++mt) { const bf16x8 a = *(const bf16x8*)(ap + (size_t)(16 * mt) * D + ks * 32);
;             acc[mt] = __builtin_amdgcn_mfma_f32_16x16x32_bf16(a, b, acc[mt], 0, 0, 0); }
;     }
; #pragma unroll
;     for (int mt = 0; mt < 4; ++mt)
; #pragma unroll
;         for (int r = 0; r < 4; ++r) part[(wave * 64 + 16 * mt + 4 * fq + r) * 16 + fr] = acc[mt][r];
;     __syncthreads();
.LBB0_417:
	v_mov_b32_e32 v38, v168
	v_readlane_b32 s24, v249, 59
	v_and_b32_e32 v39, 15, v38
	s_waitcnt vmcnt(22)
	v_lshl_or_b32 v4, s2, 6, v39
	v_lshlrev_b32_e32 v41, 2, v38
	v_ashrrev_i32_e32 v5, 31, v4
	v_and_b32_e32 v6, 0xffffff00, v41
	v_lshlrev_b64 v[4:5], 12, v[4:5]
	v_ashrrev_i32_e32 v7, 31, v6
	s_waitcnt vmcnt(21)
	v_lshlrev_b32_e32 v8, 12, v39
	v_mov_b32_e32 v9, v137
	v_readlane_b32 s25, v249, 60
	v_bfe_u32 v40, v38, 4, 2
	v_lshl_add_u64 v[4:5], s[90:91], 0, v[4:5]
	v_lshlrev_b64 v[6:7], 1, v[6:7]
	v_lshl_add_u64 v[8:9], s[24:25], 0, v[8:9]
	v_lshl_add_u64 v[4:5], v[4:5], 0, v[6:7]
	v_lshlrev_b32_e32 v136, 4, v40
	v_lshl_add_u64 v[6:7], v[8:9], 0, v[6:7]
	s_waitcnt vmcnt(20)
	v_lshl_add_u64 v[12:13], v[6:7], 0, v[136:137]
	v_lshl_add_u64 v[4:5], v[4:5], 0, v[136:137]
	s_mov_b32 s3, 0x10000
	v_add_co_u32_e32 v6, vcc, s3, v4
	s_mov_b32 s3, 0x20000
	s_nop 0
	v_addc_co_u32_e32 v7, vcc, 0, v5, vcc
	v_add_co_u32_e32 v8, vcc, s3, v4
	s_mov_b32 s3, 0x30000
	s_nop 0
	v_addc_co_u32_e32 v9, vcc, 0, v5, vcc
	v_add_co_u32_e32 v10, vcc, s3, v4
	s_nop 1
	v_addc_co_u32_e32 v11, vcc, 0, v5, vcc
	global_load_dwordx4 v[50:53], v[12:13], off
	global_load_dwordx4 v[54:57], v[4:5], off
	global_load_dwordx4 v[58:61], v[6:7], off
	global_load_dwordx4 v[62:65], v[8:9], off
	global_load_dwordx4 v[66:69], v[10:11], off
	global_load_dwordx4 v[70:73], v[12:13], off offset:64
	global_load_dwordx4 v[74:77], v[4:5], off offset:64
	global_load_dwordx4 v[78:81], v[6:7], off offset:64
	global_load_dwordx4 v[82:85], v[8:9], off offset:64
	global_load_dwordx4 v[86:89], v[10:11], off offset:64
	global_load_dwordx4 v[90:93], v[12:13], off offset:128
	global_load_dwordx4 v[94:97], v[4:5], off offset:128
	global_load_dwordx4 v[98:101], v[6:7], off offset:128
	global_load_dwordx4 v[102:105], v[8:9], off offset:128
	global_load_dwordx4 v[106:109], v[10:11], off offset:128
	global_load_dwordx4 v[110:113], v[12:13], off offset:192
	global_load_dwordx4 v[114:117], v[4:5], off offset:192
	global_load_dwordx4 v[118:121], v[6:7], off offset:192
	global_load_dwordx4 v[122:125], v[8:9], off offset:192
	global_load_dwordx4 v[126:129], v[10:11], off offset:192
	global_load_dwordx4 v[198:201], v[12:13], off offset:256
	global_load_dwordx4 v[202:205], v[4:5], off offset:256
	global_load_dwordx4 v[206:209], v[6:7], off offset:256
	global_load_dwordx4 v[210:213], v[8:9], off offset:256
	global_load_dwordx4 v[214:217], v[10:11], off offset:256
	global_load_dwordx4 v[218:221], v[12:13], off offset:320
	global_load_dwordx4 v[222:225], v[4:5], off offset:320
	global_load_dwordx4 v[226:229], v[6:7], off offset:320
	global_load_dwordx4 v[230:233], v[8:9], off offset:320
	global_load_dwordx4 v[234:237], v[10:11], off offset:320
	v_mov_b32_e32 v48, v168
	v_readlane_b32 s28, v247, 52
	v_readlane_b32 s29, v247, 53
	s_movk_i32 s20, 0x210
	v_mov_b32_e32 v47, v137
	s_mov_b64 s[88:89], 0
	s_mov_b32 s30, s86
	s_ashr_i32 s3, s2, 31
	s_lshl_b64 s[24:25], s[2:3], 6
	s_movk_i32 s3, 0x1000
	s_waitcnt vmcnt(20)
	v_mfma_f32_16x16x32_bf16 v[18:21], v[54:57], v[50:53], 0
	v_mfma_f32_16x16x32_bf16 v[30:33], v[58:61], v[50:53], 0
	v_mfma_f32_16x16x32_bf16 v[22:25], v[62:65], v[50:53], 0
	v_mfma_f32_16x16x32_bf16 v[34:37], v[66:69], v[50:53], 0
	v_mfma_f32_16x16x32_bf16 v[18:21], v[74:77], v[70:73], v[18:21]
	v_mfma_f32_16x16x32_bf16 v[30:33], v[78:81], v[70:73], v[30:33]
	v_mfma_f32_16x16x32_bf16 v[22:25], v[82:85], v[70:73], v[22:25]
	v_mfma_f32_16x16x32_bf16 v[34:37], v[86:89], v[70:73], v[34:37]
	global_load_dwordx4 v[50:53], v[12:13], off offset:384
	global_load_dwordx4 v[54:57], v[4:5], off offset:384
	global_load_dwordx4 v[58:61], v[6:7], off offset:384
	global_load_dwordx4 v[62:65], v[8:9], off offset:384
	global_load_dwordx4 v[66:69], v[10:11], off offset:384
	global_load_dwordx4 v[70:73], v[12:13], off offset:448
	global_load_dwordx4 v[74:77], v[4:5], off offset:448
	global_load_dwordx4 v[78:81], v[6:7], off offset:448
	global_load_dwordx4 v[82:85], v[8:9], off offset:448
	global_load_dwordx4 v[86:89], v[10:11], off offset:448
	s_waitcnt vmcnt(20)
	v_mfma_f32_16x16x32_bf16 v[18:21], v[94:97], v[90:93], v[18:21]
	v_mfma_f32_16x16x32_bf16 v[30:33], v[98:101], v[90:93], v[30:33]
	v_mfma_f32_16x16x32_bf16 v[22:25], v[102:105], v[90:93], v[22:25]
	v_mfma_f32_16x16x32_bf16 v[34:37], v[106:109], v[90:93], v[34:37]
	v_mfma_f32_16x16x32_bf16 v[18:21], v[114:117], v[110:113], v[18:21]
	v_mfma_f32_16x16x32_bf16 v[30:33], v[118:121], v[110:113], v[30:33]
	v_mfma_f32_16x16x32_bf16 v[22:25], v[122:125], v[110:113], v[22:25]
	v_mfma_f32_16x16x32_bf16 v[34:37], v[126:129], v[110:113], v[34:37]
	s_waitcnt vmcnt(10)
	v_mfma_f32_16x16x32_bf16 v[18:21], v[202:205], v[198:201], v[18:21]
	v_mfma_f32_16x16x32_bf16 v[30:33], v[206:209], v[198:201], v[30:33]
	v_mfma_f32_16x16x32_bf16 v[22:25], v[210:213], v[198:201], v[22:25]
	v_mfma_f32_16x16x32_bf16 v[34:37], v[214:217], v[198:201], v[34:37]
	v_mfma_f32_16x16x32_bf16 v[18:21], v[222:225], v[218:221], v[18:21]
	v_mfma_f32_16x16x32_bf16 v[30:33], v[226:229], v[218:221], v[30:33]
	v_mfma_f32_16x16x32_bf16 v[22:25], v[230:233], v[218:221], v[22:25]
	v_mfma_f32_16x16x32_bf16 v[34:37], v[234:237], v[218:221], v[34:37]
	s_waitcnt vmcnt(0)
	v_mfma_f32_16x16x32_bf16 v[18:21], v[54:57], v[50:53], v[18:21]
	v_mfma_f32_16x16x32_bf16 v[30:33], v[58:61], v[50:53], v[30:33]
	v_mfma_f32_16x16x32_bf16 v[22:25], v[62:65], v[50:53], v[22:25]
	v_mfma_f32_16x16x32_bf16 v[34:37], v[66:69], v[50:53], v[34:37]
	v_mfma_f32_16x16x32_bf16 v[18:21], v[74:77], v[70:73], v[18:21]
	v_mfma_f32_16x16x32_bf16 v[4:7], v[78:81], v[70:73], v[30:33]
	v_mfma_f32_16x16x32_bf16 v[22:25], v[82:85], v[70:73], v[22:25]
	v_mfma_f32_16x16x32_bf16 v[8:11], v[86:89], v[70:73], v[34:37]
	v_lshl_add_u32 v12, v39, 2, 0
	v_lshlrev_b32_e32 v13, 8, v40
	v_lshlrev_b32_e32 v14, 6, v38
	v_and_b32_e32 v14, 0xfffff000, v14
	v_add3_u32 v12, v12, v13, v14
	s_nop 7
	v_add_u32_e32 v13, 0xbc00, v12
	ds_write2_b32 v13, v18, v19 offset0:128 offset1:144
	ds_write2_b32 v13, v20, v21 offset0:160 offset1:176
	v_add_u32_e32 v13, 0xc000, v12
	ds_write2_b32 v13, v4, v5 offset0:128 offset1:144
	ds_write2_b32 v13, v6, v7 offset0:160 offset1:176
	v_add_u32_e32 v4, 0xc400, v12
	s_nop 0
	ds_write2_b32 v4, v22, v23 offset0:128 offset1:144
	ds_write2_b32 v4, v24, v25 offset0:160 offset1:176
	v_add_u32_e32 v4, 0xc800, v12
	v_add_u32_e32 v14, 0, v41
	ds_write2_b32 v4, v8, v9 offset0:128 offset1:144
	ds_write2_b32 v4, v10, v11 offset0:160 offset1:176
	s_waitcnt lgkmcnt(0)
	s_barrier
; #define LAS __attribute__((address_space(3)))
; __device__ __forceinline__ void gla_zl_chunk(const bf16* XN, const bf16* WzlT  , LAS unsigned char* lds, int c, int tid_in) {
;     ...
;     for (int i = 0; i < 2; ++i) { const int o = tid + NTHR * i; float s = 0.f;
; #pragma unroll
;         for (int w = 0; w < 8; ++w) s += part[w * 1024 + o];
;         zl_s[o] = s; }
;     __syncthreads();
; }
; __device__ __forceinline__ G1In gla1_load(const bf16* proj, const float* gw2, const float* gbias, size_t row0, int hd, int tid) {
;     G1In in;
;     { const int idx = tid * 4, r = idx >> 7, k = idx & 127; in.w2 = *(const f32x4*)(gw2 + r * DQK + hd * HK + k); }
;     in.gb = gbias[hd * HK + (tid & 127)];
;     const int ps0 = (tid & 31) * 2, pk0 = (tid >> 5) * 8;
;     in.ka = *(const u32x4*)(proj + (row0 + ps0) * NIN + C_K + hd * HK + pk0); in.kb = *(const u32x4*)(proj + (row0 + ps0 + 1) * NIN + C_K + hd * HK + pk0);
; #pragma unroll
;     for (int it = 0; it < 2; ++it) { const int item = tid + NTHR * it, s0 = (item & 31) * 2, v0 = (item >> 5) * 8;
;         in.vpa[it] = *(const u32x4*)(proj + (row0 + s0) * NIN + C_V + hd * HV + v0); in.vpb[it] = *(const u32x4*)(proj + (row0 + s0 + 1) * NIN + C_V + hd * HV + v0); }
;     return in;
; }
; __device__ __forceinline__ void gla1_chunk(const bf16* proj, const float* gw2  , const float* gbias  , bf16* U, float* BC, float* DEC,
;                                            LAS unsigned char* lds, int c, int tid_in) {
;     int tid = tid_in; asm volatile("" : "+v"(tid));
;     LAS float* zl_s = (LAS float*)lds;
;     LAS float* w2_s = (LAS float*)(lds + 4096);
;     LAS float* gb_s = (LAS float*)(lds + 12288);
;     LAS float* seg_s = (LAS float*)(lds + 12800);
;     LAS float* bc_s = (LAS float*)(lds + 14848);
;     LAS bf16* kT_s = (LAS bf16*)(lds + 48640);
;     LAS bf16* vT_s = (LAS bf16*)(lds + 67072);
;     const int lane = tid & 63, wave = tid >> 6, fr = lane & 15, fq = lane >> 4;
;     const size_t row0 = (size_t)c * CH;
;     G1In in = gla1_load(proj, gw2, gbias, row0, 0, tid);
	ds_read2st64_b32 v[4:5], v14 offset0:190 offset1:198
	ds_read2st64_b32 v[6:7], v14 offset0:206 offset1:214
	ds_read2st64_b32 v[8:9], v14 offset0:222 offset1:230
	ds_read2st64_b32 v[10:11], v14 offset0:238 offset1:246
	v_add_u32_e32 v15, 0xbe00, v14
	s_waitcnt lgkmcnt(3)
	v_add_f32_e32 v4, 0, v4
	s_waitcnt lgkmcnt(2)
	v_add_f32_e32 v4, v4, v6
	ds_read_b32 v6, v14 offset:65024
	s_waitcnt lgkmcnt(2)
	v_add_f32_e32 v4, v4, v8
	ds_read2st64_b32 v[12:13], v15 offset0:80 offset1:96
	s_waitcnt lgkmcnt(2)
	v_add_f32_e32 v4, v4, v10
	v_add_u32_e32 v8, 0xc600, v14
	s_waitcnt lgkmcnt(1)
	v_add_f32_e32 v4, v4, v6
	ds_read_b32 v6, v15 offset:28672
	s_waitcnt lgkmcnt(1)
	v_add_f32_e32 v4, v4, v12
	v_add_f32_e32 v4, v4, v13
	s_waitcnt lgkmcnt(0)
	v_add_f32_e32 v6, v4, v6
	v_add_f32_e32 v4, 0, v5
	v_add_f32_e32 v4, v4, v7
	v_add_f32_e32 v4, v4, v9
	v_add_f32_e32 v7, v4, v11
	ds_read2st64_b32 v[4:5], v8 offset0:64 offset1:80
	s_waitcnt lgkmcnt(0)
	v_add_f32_e32 v4, v7, v4
	v_add_f32_e32 v7, v4, v5
	ds_read2st64_b32 v[4:5], v8 offset0:96 offset1:112
	s_waitcnt lgkmcnt(0)
	v_add_f32_e32 v4, v7, v4
	v_add_f32_e32 v4, v4, v5
	ds_write2st64_b32 v14, v6, v4 offset1:8
	s_waitcnt lgkmcnt(0)
	s_barrier
	s_nop 0
	v_lshlrev_b32_e32 v42, 4, v48
	v_and_b32_e32 v4, 0xfffffe00, v42
	v_ashrrev_i32_e32 v5, 31, v4
	v_lshlrev_b64 v[32:33], 2, v[4:5]
	v_lshlrev_b32_e32 v8, 2, v48
	v_lshl_add_u64 v[4:5], s[28:29], 0, v[32:33]
	v_and_b32_e32 v136, 0x1f0, v42
	v_lshl_add_u64 v[4:5], v[4:5], 0, v[136:137]
	v_and_b32_e32 v136, 0x1fc, v8
	v_lshlrev_b32_e32 v8, 1, v48
	v_readlane_b32 s28, v247, 54
	v_and_b32_e32 v49, 62, v8
	v_ashrrev_i32_e32 v50, 2, v48
	v_readlane_b32 s29, v247, 55
	v_and_b32_e32 v34, -8, v50
	v_or_b32_e32 v10, s24, v49
	v_mov_b64_e32 v[8:9], s[92:93]
	v_ashrrev_i32_e32 v35, 31, v34
	v_lshlrev_b64 v[36:37], 1, v[34:35]
	global_load_dword v120, v136, s[28:29]
	v_mad_u64_u32 v[16:17], s[28:29], v10, s22, v[8:9]
	v_mad_i32_i24 v17, s25, v174, v17
	v_add_u32_e32 v26, 0x200, v48
	v_lshl_add_u64 v[12:13], v[16:17], 0, v[36:37]
	v_ashrrev_i32_e32 v26, 2, v26
	v_add_co_u32_e32 v8, vcc, s3, v12
	s_mov_b64 s[24:25], 0x2000
	v_and_b32_e32 v38, -8, v26
	v_addc_co_u32_e32 v9, vcc, 0, v13, vcc
	v_lshl_add_u64 v[24:25], v[16:17], 0, s[24:25]
	s_mov_b64 s[24:25], 0x5200
	v_ashrrev_i32_e32 v39, 31, v38
	v_add_co_u32_e32 v12, vcc, s33, v12
	v_lshl_add_u64 v[28:29], v[16:17], 0, s[24:25]
	v_lshlrev_b64 v[40:41], 1, v[38:39]
	v_addc_co_u32_e32 v13, vcc, 0, v13, vcc
	v_lshl_add_u64 v[16:17], v[24:25], 0, v[36:37]
	v_lshl_add_u64 v[20:21], v[28:29], 0, v[36:37]
	v_lshl_add_u64 v[24:25], v[24:25], 0, v[40:41]
	v_lshl_add_u64 v[28:29], v[28:29], 0, v[40:41]
	global_load_dwordx4 v[4:7], v[4:5], off
	s_movk_i32 s3, 0x80
	global_load_dwordx4 v[8:11], v[8:9], off offset:3072
	v_bfe_u32 v43, v48, 4, 2
	global_load_dwordx4 v[12:15], v[12:13], off offset:3584
	v_cmp_gt_i32_e64 s[44:45], s3, v48
	global_load_dwordx4 v[16:19], v[16:17], off
	v_lshlrev_b32_e32 v44, 2, v34
	global_load_dwordx4 v[20:23], v[20:21], off
	v_mad_u32_u24 v46, v49, s20, 0
	global_load_dwordx4 v[24:27], v[24:25], off
	s_movk_i32 s3, 0xfdf2
	global_load_dwordx4 v[28:31], v[28:29], off
	v_and_b32_e32 v45, 15, v48
	v_ashrrev_i32_e32 v35, 7, v48
	v_add_u32_e32 v124, 0, v44
	v_add_u32_e32 v125, v46, v44
	v_mad_i32_i24 v126, v49, s3, v46
	v_ashrrev_i32_e32 v44, 1, v48
	s_movk_i32 s3, 0xffe0
	v_lshlrev_b32_e32 v46, 4, v43
	v_readlane_b32 s28, v247, 30
	v_readlane_b32 s24, v249, 2
	v_add_u32_e32 v121, 0, v42
	v_lshlrev_b32_e32 v42, 4, v35
	v_and_or_b32 v44, v44, s3, v45
	v_add_u32_e32 v51, s28, v46
	v_add_u32_e32 v52, 0, v46
	v_lshlrev_b32_e32 v46, 3, v43
	v_readlane_b32 s25, v249, 3
	s_movk_i32 s3, 0x2100
	v_lshl_add_u32 v123, v35, 10, 0
	v_cmp_eq_u32_e64 s[46:47], 3, v35
	v_lshl_add_u64 v[100:101], s[24:25], 0, v[46:47]
	v_cmp_lt_i32_e64 s[48:49], 0, v35
	v_cmp_lt_i32_e64 s[50:51], 1, v35
	v_cmp_lt_i32_e64 s[52:53], 2, v35
	v_mul_lo_u32 v46, v35, s3
	v_or_b32_e32 v35, 1, v42
	v_mul_lo_u32 v47, v35, s20
	v_mul_lo_u32 v127, v34, s37
	v_lshl_add_u32 v34, v49, 1, s28
	v_or_b32_e32 v35, 7, v50
	v_add_u32_e32 v128, v127, v34
	v_mad_u64_u32 v[102:103], s[24:25], v38, s37, v[34:35]
	v_mul_u32_u24_e32 v38, 0x90, v45
	v_or_b32_e32 v34, 16, v44
	v_ashrrev_i32_e32 v45, 31, v44
	v_mul_lo_u32 v49, v35, s37
	v_mul_lo_u32 v50, v44, s37
	v_lshlrev_b64 v[104:105], 8, v[44:45]
	v_ashrrev_i32_e32 v35, 31, v34
	v_and_b32_e32 v44, 31, v48
	s_movk_i32 s3, 0x6400
	v_lshlrev_b64 v[106:107], 8, v[34:35]
	v_mad_u64_u32 v[34:35], s[24:25], v44, s3, v[36:37]
	v_lshl_add_u64 v[108:109], s[26:27], 0, v[34:35]
	v_mad_u64_u32 v[34:35], s[24:25], v44, s3, v[40:41]
	v_readlane_b32 s24, v247, 62
	v_readlane_b32 s25, v247, 63
	v_ashrrev_i32_e32 v43, 31, v42
	v_lshl_or_b32 v32, v44, 4, v32
	v_lshl_add_u64 v[112:113], s[24:25], 0, v[136:137]
	v_readlane_b32 s24, v246, 0
	v_readlane_b32 s25, v246, 1
	v_add_u32_e32 v122, 0, v136
	v_mul_lo_u32 v39, v48, -12
	v_lshl_add_u64 v[114:115], s[24:25], 0, v[32:33]
	v_lshlrev_b64 v[32:33], 11, v[42:43]
	v_or_b32_e32 v32, v32, v136
	v_add_u32_e32 v129, 0x120, v128
	v_add_u32_e32 v130, 0x240, v128
	v_add_u32_e32 v131, 0x360, v128
	v_lshl_add_u64 v[110:111], s[26:27], 0, v[34:35]
	v_lshl_add_u64 v[116:117], s[4:5], 0, v[32:33]
	v_lshl_add_u64 v[118:119], s[42:43], 0, v[136:137]
	v_add_u32_e32 v103, v122, v46
	v_add_u32_e32 v136, v122, v47
	v_add_u32_e32 v150, v126, v49
	v_add_u32_e32 v151, v51, v50
	v_add_u32_e32 v152, v52, v38
	v_add_u32_e32 v153, v121, v39
	s_mov_b64 s[24:25], 0
	s_waitcnt vmcnt(6)
	s_branch .LBB0_419

; #define LAS __attribute__((address_space(3)))
; __device__ __forceinline__ float logsig(float z) { return fminf(z, 0.f) - __logf(1.0f + __expf(-fabsf(z))); }
; __device__ __forceinline__ void gla1_chunk(const bf16* proj, const float* gw2  , const float* gbias  , bf16* U, float* BC, float* DEC,
;                                            LAS unsigned char* lds, int c, int tid_in) {
;     ...
;         *(LAS f32x4*)(w2_s + tid * 4) = in.w2;
;         if (tid < 128) gb_s[tid] = in.gb;
;         __syncthreads();
;         const int k = tid & 127, tq = tid >> 7;
;         {
;             float w[16], pre[16]; const float bias = gb_s[k];
; #pragma unroll
;             for (int r = 0; r < 16; ++r) w[r] = w2_s[r * 128 + k];
;             float run = 0.f;
; #pragma unroll
;             for (int i = 0; i < 16; ++i) { const int t = 16 * tq + i; float z = bias;
;                 const f32x4 z0 = *(const LAS f32x4*)(zl_s + t * 16), z1 = *(const LAS f32x4*)(zl_s + t * 16 + 4), z2 = *(const LAS f32x4*)(zl_s + t * 16 + 8), z3 = *(const LAS f32x4*)(zl_s + t * 16 + 12);
; #pragma unroll
;                 for (int r = 0; r < 4; ++r) { z += z0[r] * w[r]; }
; #pragma unroll
;                 for (int r = 0; r < 4; ++r) { z += z1[r] * w[4 + r]; }
; #pragma unroll
;                 for (int r = 0; r < 4; ++r) { z += z2[r] * w[8 + r]; }
; #pragma unroll
;                 for (int r = 0; r < 4; ++r) { z += z3[r] * w[12 + r]; }
;                 run += logsig(z) * (1.0f / 16.0f); pre[i] = run; }
.LBB0_419:
	s_waitcnt vmcnt(22)
	ds_write_b128 v121, v[4:7] offset:4096
	s_and_saveexec_b64 s[54:55], s[44:45]
	ds_write_b32 v153, v120 offset:12288
	s_or_b64 exec, exec, s[54:55]
	s_waitcnt lgkmcnt(0)
	s_barrier
	ds_read_b32 v49, v122 offset:12288
	ds_read2st64_b32 v[46:47], v122 offset0:16 offset1:18
	ds_read2st64_b32 v[44:45], v122 offset0:20 offset1:22
	ds_read2st64_b32 v[42:43], v122 offset0:24 offset1:26
	ds_read2st64_b32 v[40:41], v122 offset0:28 offset1:30
	ds_read2st64_b32 v[38:39], v122 offset0:32 offset1:34
	ds_read2st64_b32 v[36:37], v122 offset0:36 offset1:38
	ds_read2st64_b32 v[34:35], v122 offset0:40 offset1:42
	ds_read2st64_b32 v[32:33], v122 offset0:44 offset1:46
	ds_read_b128 v[50:53], v123
	ds_read_b128 v[54:57], v123 offset:16
	ds_read_b128 v[58:61], v123 offset:32
	ds_read_b128 v[62:65], v123 offset:48
	s_mov_b32 s3, 0x3d800000
	s_waitcnt lgkmcnt(3)
	v_fma_f32 v48, v46, v50, v49
	v_fmac_f32_e32 v48, v47, v51
	v_fmac_f32_e32 v48, v44, v52
	v_fmac_f32_e32 v48, v45, v53
	s_waitcnt lgkmcnt(2)
	v_fmac_f32_e32 v48, v42, v54
	v_fmac_f32_e32 v48, v43, v55
	v_fmac_f32_e32 v48, v40, v56
	v_fmac_f32_e32 v48, v41, v57
	s_waitcnt lgkmcnt(1)
	v_fmac_f32_e32 v48, v38, v58
	v_fmac_f32_e32 v48, v39, v59
	v_fmac_f32_e32 v48, v36, v60
	v_fmac_f32_e32 v48, v37, v61
	s_waitcnt lgkmcnt(0)
	v_fmac_f32_e32 v48, v34, v62
	v_fmac_f32_e32 v48, v35, v63
	v_fmac_f32_e32 v48, v32, v64
	v_fmac_f32_e32 v48, v33, v65
	v_min_f32_e32 v50, 0, v48
	v_mul_f32_e64 v48, |v48|, s36
	v_exp_f32_e32 v48, v48
	s_nop 0
	v_add_f32_e32 v48, 1.0, v48
	v_cmp_gt_f32_e32 vcc, s15, v48
	s_nop 1
	v_cndmask_b32_e64 v51, 0, 32, vcc
	v_ldexp_f32 v48, v48, v51
	v_log_f32_e32 v48, v48
	s_nop 0
	v_mul_f32_e32 v51, 0x3f317217, v48
	v_fma_f32 v51, v48, s16, -v51
	v_fmac_f32_e32 v51, 0x3377d1cf, v48
	v_fmac_f32_e32 v51, 0x3f317217, v48
	v_cmp_lt_f32_e64 s[54:55], |v48|, s17
	s_nop 1
	v_cndmask_b32_e64 v48, v48, v51, s[54:55]
	v_cndmask_b32_e32 v51, 0, v175, vcc
	v_sub_f32_e32 v48, v48, v51
	v_sub_f32_e32 v48, v50, v48
	ds_read_b128 v[50:53], v123 offset:64
	ds_read_b128 v[54:57], v123 offset:80
	ds_read_b128 v[58:61], v123 offset:96
	ds_read_b128 v[62:65], v123 offset:112
	v_fma_f32 v48, v48, s3, 0
	s_waitcnt lgkmcnt(3)
	v_fma_f32 v50, v46, v50, v49
	v_fmac_f32_e32 v50, v47, v51
	v_fmac_f32_e32 v50, v44, v52
	v_fmac_f32_e32 v50, v45, v53
	s_waitcnt lgkmcnt(2)
	v_fmac_f32_e32 v50, v42, v54
	v_fmac_f32_e32 v50, v43, v55
	v_fmac_f32_e32 v50, v40, v56
	v_fmac_f32_e32 v50, v41, v57
	s_waitcnt lgkmcnt(1)
	v_fmac_f32_e32 v50, v38, v58
	v_fmac_f32_e32 v50, v39, v59
	v_fmac_f32_e32 v50, v36, v60
	v_fmac_f32_e32 v50, v37, v61
	s_waitcnt lgkmcnt(0)
	v_fmac_f32_e32 v50, v34, v62
	v_fmac_f32_e32 v50, v35, v63
	v_fmac_f32_e32 v50, v32, v64
	v_fmac_f32_e32 v50, v33, v65
	v_min_f32_e32 v51, 0, v50
	v_mul_f32_e64 v50, |v50|, s36
	v_exp_f32_e32 v50, v50
	s_nop 0
	v_add_f32_e32 v50, 1.0, v50
	v_cmp_gt_f32_e32 vcc, s15, v50
	s_nop 1
	v_cndmask_b32_e64 v52, 0, 32, vcc
	v_ldexp_f32 v50, v50, v52
	v_log_f32_e32 v50, v50
	s_nop 0
	v_mul_f32_e32 v52, 0x3f317217, v50
	v_fma_f32 v52, v50, s16, -v52
	v_fmac_f32_e32 v52, 0x3377d1cf, v50
	v_fmac_f32_e32 v52, 0x3f317217, v50
	v_cmp_lt_f32_e64 s[54:55], |v50|, s17
	s_nop 1
	v_cndmask_b32_e64 v50, v50, v52, s[54:55]
	v_cndmask_b32_e32 v52, 0, v175, vcc
	v_sub_f32_e32 v50, v50, v52
	ds_read_b128 v[52:55], v123 offset:128
	ds_read_b128 v[56:59], v123 offset:144
	ds_read_b128 v[60:63], v123 offset:160
	ds_read_b128 v[64:67], v123 offset:176
	v_sub_f32_e32 v50, v51, v50
	s_waitcnt lgkmcnt(3)
	v_fma_f32 v51, v46, v52, v49
	v_fmac_f32_e32 v51, v47, v53
	v_fmac_f32_e32 v51, v44, v54
	v_fmac_f32_e32 v51, v45, v55
	s_waitcnt lgkmcnt(2)
	v_fmac_f32_e32 v51, v42, v56
	v_fmac_f32_e32 v51, v43, v57
	v_fmac_f32_e32 v51, v40, v58
	v_fmac_f32_e32 v51, v41, v59
	s_waitcnt lgkmcnt(1)
	v_fmac_f32_e32 v51, v38, v60
	v_fmac_f32_e32 v51, v39, v61
	v_fmac_f32_e32 v51, v36, v62
	v_fmac_f32_e32 v51, v37, v63
	s_waitcnt lgkmcnt(0)
	v_fmac_f32_e32 v51, v34, v64
	v_fmac_f32_e32 v51, v35, v65
	v_fmac_f32_e32 v51, v32, v66
	v_fmac_f32_e32 v51, v33, v67
	v_min_f32_e32 v52, 0, v51
	v_mul_f32_e64 v51, |v51|, s36
	v_exp_f32_e32 v51, v51
	v_fmamk_f32 v50, v50, 0x3d800000, v48
	v_add_f32_e32 v51, 1.0, v51
	v_cmp_gt_f32_e32 vcc, s15, v51
	s_nop 1
	v_cndmask_b32_e64 v53, 0, 32, vcc
	v_ldexp_f32 v51, v51, v53
	v_log_f32_e32 v51, v51
	s_nop 0
	v_mul_f32_e32 v53, 0x3f317217, v51
	v_fma_f32 v53, v51, s16, -v53
	v_fmac_f32_e32 v53, 0x3377d1cf, v51
	v_fmac_f32_e32 v53, 0x3f317217, v51
	v_cmp_lt_f32_e64 s[54:55], |v51|, s17
	s_nop 1
	v_cndmask_b32_e64 v51, v51, v53, s[54:55]
	v_cndmask_b32_e32 v53, 0, v175, vcc
	v_sub_f32_e32 v51, v51, v53
	v_sub_f32_e32 v51, v52, v51
	ds_read_b128 v[52:55], v123 offset:192
	ds_read_b128 v[56:59], v123 offset:208
	ds_read_b128 v[60:63], v123 offset:224
	ds_read_b128 v[64:67], v123 offset:240
	v_fmamk_f32 v51, v51, 0x3d800000, v50
	s_waitcnt lgkmcnt(3)
	v_fma_f32 v52, v46, v52, v49
	v_fmac_f32_e32 v52, v47, v53
	v_fmac_f32_e32 v52, v44, v54
	v_fmac_f32_e32 v52, v45, v55
	s_waitcnt lgkmcnt(2)
	v_fmac_f32_e32 v52, v42, v56
	v_fmac_f32_e32 v52, v43, v57
	v_fmac_f32_e32 v52, v40, v58
	v_fmac_f32_e32 v52, v41, v59
	s_waitcnt lgkmcnt(1)
	v_fmac_f32_e32 v52, v38, v60
	v_fmac_f32_e32 v52, v39, v61
	v_fmac_f32_e32 v52, v36, v62
	v_fmac_f32_e32 v52, v37, v63
	s_waitcnt lgkmcnt(0)
; #define LAS __attribute__((address_space(3)))
; __device__ __forceinline__ float logsig(float z) { return fminf(z, 0.f) - __logf(1.0f + __expf(-fabsf(z))); }
; __device__ __forceinline__ void gla1_chunk(const bf16* proj, const float* gw2  , const float* gbias  , bf16* U, float* BC, float* DEC,
;                                            LAS unsigned char* lds, int c, int tid_in) {
;     ...
;             for (int i = 0; i < 16; ++i) { const int t = 16 * tq + i; float z = bias;
;                 const f32x4 z0 = *(const LAS f32x4*)(zl_s + t * 16), z1 = *(const LAS f32x4*)(zl_s + t * 16 + 4), z2 = *(const LAS f32x4*)(zl_s + t * 16 + 8), z3 = *(const LAS f32x4*)(zl_s + t * 16 + 12);
; #pragma unroll
;                 for (int r = 0; r < 4; ++r) { z += z0[r] * w[r]; }
; #pragma unroll
;                 for (int r = 0; r < 4; ++r) { z += z1[r] * w[4 + r]; }
; #pragma unroll
;                 for (int r = 0; r < 4; ++r) { z += z2[r] * w[8 + r]; }
; #pragma unroll
;                 for (int r = 0; r < 4; ++r) { z += z3[r] * w[12 + r]; }
;                 run += logsig(z) * (1.0f / 16.0f); pre[i] = run; }
	v_fmac_f32_e32 v52, v34, v64
	v_fmac_f32_e32 v52, v35, v65
	v_fmac_f32_e32 v52, v32, v66
	v_fmac_f32_e32 v52, v33, v67
	v_min_f32_e32 v53, 0, v52
	v_mul_f32_e64 v52, |v52|, s36
	v_exp_f32_e32 v52, v52
	s_nop 0
	v_add_f32_e32 v52, 1.0, v52
	v_cmp_gt_f32_e32 vcc, s15, v52
	s_nop 1
	v_cndmask_b32_e64 v54, 0, 32, vcc
	v_ldexp_f32 v52, v52, v54
	v_log_f32_e32 v52, v52
	s_nop 0
	v_mul_f32_e32 v54, 0x3f317217, v52
	v_fma_f32 v54, v52, s16, -v54
	v_fmac_f32_e32 v54, 0x3377d1cf, v52
	v_fmac_f32_e32 v54, 0x3f317217, v52
	v_cmp_lt_f32_e64 s[54:55], |v52|, s17
	s_nop 1
	v_cndmask_b32_e64 v52, v52, v54, s[54:55]
	v_cndmask_b32_e32 v54, 0, v175, vcc
	v_sub_f32_e32 v52, v52, v54
	ds_read_b128 v[54:57], v123 offset:256
	ds_read_b128 v[58:61], v123 offset:272
	ds_read_b128 v[62:65], v123 offset:288
	ds_read_b128 v[66:69], v123 offset:304
	v_sub_f32_e32 v52, v53, v52
	s_waitcnt lgkmcnt(3)
	v_fma_f32 v53, v46, v54, v49
	v_fmac_f32_e32 v53, v47, v55
	v_fmac_f32_e32 v53, v44, v56
	v_fmac_f32_e32 v53, v45, v57
	s_waitcnt lgkmcnt(2)
	v_fmac_f32_e32 v53, v42, v58
	v_fmac_f32_e32 v53, v43, v59
	v_fmac_f32_e32 v53, v40, v60
	v_fmac_f32_e32 v53, v41, v61
	s_waitcnt lgkmcnt(1)
	v_fmac_f32_e32 v53, v38, v62
	v_fmac_f32_e32 v53, v39, v63
	v_fmac_f32_e32 v53, v36, v64
	v_fmac_f32_e32 v53, v37, v65
	s_waitcnt lgkmcnt(0)
	v_fmac_f32_e32 v53, v34, v66
	v_fmac_f32_e32 v53, v35, v67
	v_fmac_f32_e32 v53, v32, v68
	v_fmac_f32_e32 v53, v33, v69
	v_min_f32_e32 v54, 0, v53
	v_mul_f32_e64 v53, |v53|, s36
	v_exp_f32_e32 v53, v53
	v_fmamk_f32 v52, v52, 0x3d800000, v51
	v_add_f32_e32 v53, 1.0, v53
	v_cmp_gt_f32_e32 vcc, s15, v53
	s_nop 1
	v_cndmask_b32_e64 v55, 0, 32, vcc
	v_ldexp_f32 v53, v53, v55
	v_log_f32_e32 v53, v53
	s_nop 0
	v_mul_f32_e32 v55, 0x3f317217, v53
	v_fma_f32 v55, v53, s16, -v55
	v_fmac_f32_e32 v55, 0x3377d1cf, v53
	v_fmac_f32_e32 v55, 0x3f317217, v53
	v_cmp_lt_f32_e64 s[54:55], |v53|, s17
	s_nop 1
	v_cndmask_b32_e64 v53, v53, v55, s[54:55]
	v_cndmask_b32_e32 v55, 0, v175, vcc
	v_sub_f32_e32 v53, v53, v55
	v_sub_f32_e32 v53, v54, v53
	ds_read_b128 v[54:57], v123 offset:320
	ds_read_b128 v[58:61], v123 offset:336
	ds_read_b128 v[62:65], v123 offset:352
	ds_read_b128 v[66:69], v123 offset:368
	v_fmamk_f32 v53, v53, 0x3d800000, v52
	s_waitcnt lgkmcnt(3)
	v_fma_f32 v54, v46, v54, v49
	v_fmac_f32_e32 v54, v47, v55
	v_fmac_f32_e32 v54, v44, v56
	v_fmac_f32_e32 v54, v45, v57
	s_waitcnt lgkmcnt(2)
	v_fmac_f32_e32 v54, v42, v58
	v_fmac_f32_e32 v54, v43, v59
	v_fmac_f32_e32 v54, v40, v60
	v_fmac_f32_e32 v54, v41, v61
	s_waitcnt lgkmcnt(1)
	v_fmac_f32_e32 v54, v38, v62
	v_fmac_f32_e32 v54, v39, v63
	v_fmac_f32_e32 v54, v36, v64
	v_fmac_f32_e32 v54, v37, v65
	s_waitcnt lgkmcnt(0)
	v_fmac_f32_e32 v54, v34, v66
	v_fmac_f32_e32 v54, v35, v67
	v_fmac_f32_e32 v54, v32, v68
	v_fmac_f32_e32 v54, v33, v69
	v_min_f32_e32 v55, 0, v54
	v_mul_f32_e64 v54, |v54|, s36
	v_exp_f32_e32 v54, v54
	s_nop 0
	v_add_f32_e32 v54, 1.0, v54
	v_cmp_gt_f32_e32 vcc, s15, v54
	s_nop 1
	v_cndmask_b32_e64 v56, 0, 32, vcc
	v_ldexp_f32 v54, v54, v56
	v_log_f32_e32 v54, v54
	s_nop 0
	v_mul_f32_e32 v56, 0x3f317217, v54
	v_fma_f32 v56, v54, s16, -v56
	v_fmac_f32_e32 v56, 0x3377d1cf, v54
	v_fmac_f32_e32 v56, 0x3f317217, v54
	v_cmp_lt_f32_e64 s[54:55], |v54|, s17
	s_nop 1
	v_cndmask_b32_e64 v54, v54, v56, s[54:55]
	v_cndmask_b32_e32 v56, 0, v175, vcc
	v_sub_f32_e32 v54, v54, v56
	ds_read_b128 v[56:59], v123 offset:384
	ds_read_b128 v[60:63], v123 offset:400
	ds_read_b128 v[64:67], v123 offset:416
	ds_read_b128 v[68:71], v123 offset:432
	v_sub_f32_e32 v54, v55, v54
	s_waitcnt lgkmcnt(3)
	v_fma_f32 v55, v46, v56, v49
	v_fmac_f32_e32 v55, v47, v57
	v_fmac_f32_e32 v55, v44, v58
	v_fmac_f32_e32 v55, v45, v59
	s_waitcnt lgkmcnt(2)
	v_fmac_f32_e32 v55, v42, v60
	v_fmac_f32_e32 v55, v43, v61
	v_fmac_f32_e32 v55, v40, v62
	v_fmac_f32_e32 v55, v41, v63
	s_waitcnt lgkmcnt(1)
	v_fmac_f32_e32 v55, v38, v64
	v_fmac_f32_e32 v55, v39, v65
	v_fmac_f32_e32 v55, v36, v66
	v_fmac_f32_e32 v55, v37, v67
	s_waitcnt lgkmcnt(0)
	v_fmac_f32_e32 v55, v34, v68
	v_fmac_f32_e32 v55, v35, v69
	v_fmac_f32_e32 v55, v32, v70
	v_fmac_f32_e32 v55, v33, v71
	v_min_f32_e32 v56, 0, v55
	v_mul_f32_e64 v55, |v55|, s36
	v_exp_f32_e32 v55, v55
	v_fmamk_f32 v54, v54, 0x3d800000, v53
	v_add_f32_e32 v55, 1.0, v55
	v_cmp_gt_f32_e32 vcc, s15, v55
	s_nop 1
	v_cndmask_b32_e64 v57, 0, 32, vcc
	v_ldexp_f32 v55, v55, v57
	v_log_f32_e32 v55, v55
	s_nop 0
	v_mul_f32_e32 v57, 0x3f317217, v55
	v_fma_f32 v57, v55, s16, -v57
	v_fmac_f32_e32 v57, 0x3377d1cf, v55
	v_fmac_f32_e32 v57, 0x3f317217, v55
	v_cmp_lt_f32_e64 s[54:55], |v55|, s17
	s_nop 1
	v_cndmask_b32_e64 v55, v55, v57, s[54:55]
	v_cndmask_b32_e32 v57, 0, v175, vcc
	v_sub_f32_e32 v55, v55, v57
	v_sub_f32_e32 v55, v56, v55
	ds_read_b128 v[56:59], v123 offset:448
	ds_read_b128 v[60:63], v123 offset:464
	ds_read_b128 v[64:67], v123 offset:480
	ds_read_b128 v[68:71], v123 offset:496
	v_fmamk_f32 v55, v55, 0x3d800000, v54
	s_waitcnt lgkmcnt(3)
	v_fma_f32 v56, v46, v56, v49
	v_fmac_f32_e32 v56, v47, v57
	v_fmac_f32_e32 v56, v44, v58
	v_fmac_f32_e32 v56, v45, v59
	s_waitcnt lgkmcnt(2)
	v_fmac_f32_e32 v56, v42, v60
	v_fmac_f32_e32 v56, v43, v61
	v_fmac_f32_e32 v56, v40, v62
	v_fmac_f32_e32 v56, v41, v63
	s_waitcnt lgkmcnt(1)
	v_fmac_f32_e32 v56, v38, v64
	v_fmac_f32_e32 v56, v39, v65
	v_fmac_f32_e32 v56, v36, v66
	v_fmac_f32_e32 v56, v37, v67
	s_waitcnt lgkmcnt(0)
; #define LAS __attribute__((address_space(3)))
; __device__ __forceinline__ float logsig(float z) { return fminf(z, 0.f) - __logf(1.0f + __expf(-fabsf(z))); }
; __device__ __forceinline__ void gla1_chunk(const bf16* proj, const float* gw2  , const float* gbias  , bf16* U, float* BC, float* DEC,
;                                            LAS unsigned char* lds, int c, int tid_in) {
;     ...
;             for (int i = 0; i < 16; ++i) { const int t = 16 * tq + i; float z = bias;
;                 const f32x4 z0 = *(const LAS f32x4*)(zl_s + t * 16), z1 = *(const LAS f32x4*)(zl_s + t * 16 + 4), z2 = *(const LAS f32x4*)(zl_s + t * 16 + 8), z3 = *(const LAS f32x4*)(zl_s + t * 16 + 12);
; #pragma unroll
;                 for (int r = 0; r < 4; ++r) { z += z0[r] * w[r]; }
; #pragma unroll
;                 for (int r = 0; r < 4; ++r) { z += z1[r] * w[4 + r]; }
; #pragma unroll
;                 for (int r = 0; r < 4; ++r) { z += z2[r] * w[8 + r]; }
; #pragma unroll
;                 for (int r = 0; r < 4; ++r) { z += z3[r] * w[12 + r]; }
;                 run += logsig(z) * (1.0f / 16.0f); pre[i] = run; }
	v_fmac_f32_e32 v56, v34, v68
	v_fmac_f32_e32 v56, v35, v69
	v_fmac_f32_e32 v56, v32, v70
	v_fmac_f32_e32 v56, v33, v71
	v_min_f32_e32 v57, 0, v56
	v_mul_f32_e64 v56, |v56|, s36
	v_exp_f32_e32 v56, v56
	s_nop 0
	v_add_f32_e32 v56, 1.0, v56
	v_cmp_gt_f32_e32 vcc, s15, v56
	s_nop 1
	v_cndmask_b32_e64 v58, 0, 32, vcc
	v_ldexp_f32 v56, v56, v58
	v_log_f32_e32 v56, v56
	s_nop 0
	v_mul_f32_e32 v58, 0x3f317217, v56
	v_fma_f32 v58, v56, s16, -v58
	v_fmac_f32_e32 v58, 0x3377d1cf, v56
	v_fmac_f32_e32 v58, 0x3f317217, v56
	v_cmp_lt_f32_e64 s[54:55], |v56|, s17
	s_nop 1
	v_cndmask_b32_e64 v56, v56, v58, s[54:55]
	v_cndmask_b32_e32 v58, 0, v175, vcc
	v_sub_f32_e32 v56, v56, v58
	ds_read_b128 v[58:61], v123 offset:512
	ds_read_b128 v[62:65], v123 offset:528
	ds_read_b128 v[66:69], v123 offset:544
	ds_read_b128 v[70:73], v123 offset:560
	v_sub_f32_e32 v56, v57, v56
	s_waitcnt lgkmcnt(3)
	v_fma_f32 v57, v46, v58, v49
	v_fmac_f32_e32 v57, v47, v59
	v_fmac_f32_e32 v57, v44, v60
	v_fmac_f32_e32 v57, v45, v61
	s_waitcnt lgkmcnt(2)
	v_fmac_f32_e32 v57, v42, v62
	v_fmac_f32_e32 v57, v43, v63
	v_fmac_f32_e32 v57, v40, v64
	v_fmac_f32_e32 v57, v41, v65
	s_waitcnt lgkmcnt(1)
	v_fmac_f32_e32 v57, v38, v66
	v_fmac_f32_e32 v57, v39, v67
	v_fmac_f32_e32 v57, v36, v68
	v_fmac_f32_e32 v57, v37, v69
	s_waitcnt lgkmcnt(0)
	v_fmac_f32_e32 v57, v34, v70
	v_fmac_f32_e32 v57, v35, v71
	v_fmac_f32_e32 v57, v32, v72
	v_fmac_f32_e32 v57, v33, v73
	v_min_f32_e32 v58, 0, v57
	v_mul_f32_e64 v57, |v57|, s36
	v_exp_f32_e32 v57, v57
	v_fmamk_f32 v56, v56, 0x3d800000, v55
	v_add_f32_e32 v57, 1.0, v57
	v_cmp_gt_f32_e32 vcc, s15, v57
	s_nop 1
	v_cndmask_b32_e64 v59, 0, 32, vcc
	v_ldexp_f32 v57, v57, v59
	v_log_f32_e32 v57, v57
	s_nop 0
	v_mul_f32_e32 v59, 0x3f317217, v57
	v_fma_f32 v59, v57, s16, -v59
	v_fmac_f32_e32 v59, 0x3377d1cf, v57
	v_fmac_f32_e32 v59, 0x3f317217, v57
	v_cmp_lt_f32_e64 s[54:55], |v57|, s17
	s_nop 1
	v_cndmask_b32_e64 v57, v57, v59, s[54:55]
	v_cndmask_b32_e32 v59, 0, v175, vcc
	v_sub_f32_e32 v57, v57, v59
	v_sub_f32_e32 v57, v58, v57
	ds_read_b128 v[58:61], v123 offset:576
	ds_read_b128 v[62:65], v123 offset:592
	ds_read_b128 v[66:69], v123 offset:608
	ds_read_b128 v[70:73], v123 offset:624
	v_fmamk_f32 v57, v57, 0x3d800000, v56
	s_waitcnt lgkmcnt(3)
	v_fma_f32 v58, v46, v58, v49
	v_fmac_f32_e32 v58, v47, v59
	v_fmac_f32_e32 v58, v44, v60
	v_fmac_f32_e32 v58, v45, v61
	s_waitcnt lgkmcnt(2)
	v_fmac_f32_e32 v58, v42, v62
	v_fmac_f32_e32 v58, v43, v63
	v_fmac_f32_e32 v58, v40, v64
	v_fmac_f32_e32 v58, v41, v65
	s_waitcnt lgkmcnt(1)
	v_fmac_f32_e32 v58, v38, v66
	v_fmac_f32_e32 v58, v39, v67
	v_fmac_f32_e32 v58, v36, v68
	v_fmac_f32_e32 v58, v37, v69
	s_waitcnt lgkmcnt(0)
	v_fmac_f32_e32 v58, v34, v70
	v_fmac_f32_e32 v58, v35, v71
	v_fmac_f32_e32 v58, v32, v72
	v_fmac_f32_e32 v58, v33, v73
	v_min_f32_e32 v59, 0, v58
	v_mul_f32_e64 v58, |v58|, s36
	v_exp_f32_e32 v58, v58
	s_nop 0
	v_add_f32_e32 v58, 1.0, v58
	v_cmp_gt_f32_e32 vcc, s15, v58
	s_nop 1
	v_cndmask_b32_e64 v60, 0, 32, vcc
	v_ldexp_f32 v58, v58, v60
	v_log_f32_e32 v58, v58
	s_nop 0
	v_mul_f32_e32 v60, 0x3f317217, v58
	v_fma_f32 v60, v58, s16, -v60
	v_fmac_f32_e32 v60, 0x3377d1cf, v58
	v_fmac_f32_e32 v60, 0x3f317217, v58
	v_cmp_lt_f32_e64 s[54:55], |v58|, s17
	s_nop 1
	v_cndmask_b32_e64 v58, v58, v60, s[54:55]
	v_cndmask_b32_e32 v60, 0, v175, vcc
	v_sub_f32_e32 v58, v58, v60
	ds_read_b128 v[60:63], v123 offset:640
	ds_read_b128 v[64:67], v123 offset:656
	ds_read_b128 v[68:71], v123 offset:672
	ds_read_b128 v[72:75], v123 offset:688
	v_sub_f32_e32 v58, v59, v58
	s_waitcnt lgkmcnt(3)
	v_fma_f32 v59, v46, v60, v49
	v_fmac_f32_e32 v59, v47, v61
	v_fmac_f32_e32 v59, v44, v62
	v_fmac_f32_e32 v59, v45, v63
	s_waitcnt lgkmcnt(2)
	v_fmac_f32_e32 v59, v42, v64
	v_fmac_f32_e32 v59, v43, v65
	v_fmac_f32_e32 v59, v40, v66
	v_fmac_f32_e32 v59, v41, v67
	s_waitcnt lgkmcnt(1)
	v_fmac_f32_e32 v59, v38, v68
	v_fmac_f32_e32 v59, v39, v69
	v_fmac_f32_e32 v59, v36, v70
	v_fmac_f32_e32 v59, v37, v71
	s_waitcnt lgkmcnt(0)
	v_fmac_f32_e32 v59, v34, v72
	v_fmac_f32_e32 v59, v35, v73
	v_fmac_f32_e32 v59, v32, v74
	v_fmac_f32_e32 v59, v33, v75
	v_min_f32_e32 v60, 0, v59
	v_mul_f32_e64 v59, |v59|, s36
	v_exp_f32_e32 v59, v59
	v_fmamk_f32 v58, v58, 0x3d800000, v57
	v_add_f32_e32 v59, 1.0, v59
	v_cmp_gt_f32_e32 vcc, s15, v59
	s_nop 1
	v_cndmask_b32_e64 v61, 0, 32, vcc
	v_ldexp_f32 v59, v59, v61
	v_log_f32_e32 v59, v59
	s_nop 0
	v_mul_f32_e32 v61, 0x3f317217, v59
	v_fma_f32 v61, v59, s16, -v61
	v_fmac_f32_e32 v61, 0x3377d1cf, v59
	v_fmac_f32_e32 v61, 0x3f317217, v59
	v_cmp_lt_f32_e64 s[54:55], |v59|, s17
	s_nop 1
	v_cndmask_b32_e64 v59, v59, v61, s[54:55]
	v_cndmask_b32_e32 v61, 0, v175, vcc
	v_sub_f32_e32 v59, v59, v61
	v_sub_f32_e32 v59, v60, v59
	ds_read_b128 v[60:63], v123 offset:704
	ds_read_b128 v[64:67], v123 offset:720
	ds_read_b128 v[68:71], v123 offset:736
	ds_read_b128 v[72:75], v123 offset:752
	v_fmamk_f32 v59, v59, 0x3d800000, v58
	s_waitcnt lgkmcnt(3)
	v_fma_f32 v60, v46, v60, v49
	v_fmac_f32_e32 v60, v47, v61
	v_fmac_f32_e32 v60, v44, v62
	v_fmac_f32_e32 v60, v45, v63
	s_waitcnt lgkmcnt(2)
	v_fmac_f32_e32 v60, v42, v64
	v_fmac_f32_e32 v60, v43, v65
	v_fmac_f32_e32 v60, v40, v66
	v_fmac_f32_e32 v60, v41, v67
	s_waitcnt lgkmcnt(1)
	v_fmac_f32_e32 v60, v38, v68
	v_fmac_f32_e32 v60, v39, v69
	v_fmac_f32_e32 v60, v36, v70
	v_fmac_f32_e32 v60, v37, v71
	s_waitcnt lgkmcnt(0)
; #define LAS __attribute__((address_space(3)))
; __device__ __forceinline__ float logsig(float z) { return fminf(z, 0.f) - __logf(1.0f + __expf(-fabsf(z))); }
; __device__ __forceinline__ void gla1_chunk(const bf16* proj, const float* gw2  , const float* gbias  , bf16* U, float* BC, float* DEC,
;                                            LAS unsigned char* lds, int c, int tid_in) {
;     ...
;             for (int i = 0; i < 16; ++i) { const int t = 16 * tq + i; float z = bias;
;                 const f32x4 z0 = *(const LAS f32x4*)(zl_s + t * 16), z1 = *(const LAS f32x4*)(zl_s + t * 16 + 4), z2 = *(const LAS f32x4*)(zl_s + t * 16 + 8), z3 = *(const LAS f32x4*)(zl_s + t * 16 + 12);
; #pragma unroll
;                 for (int r = 0; r < 4; ++r) { z += z0[r] * w[r]; }
; #pragma unroll
;                 for (int r = 0; r < 4; ++r) { z += z1[r] * w[4 + r]; }
; #pragma unroll
;                 for (int r = 0; r < 4; ++r) { z += z2[r] * w[8 + r]; }
; #pragma unroll
;                 for (int r = 0; r < 4; ++r) { z += z3[r] * w[12 + r]; }
;                 run += logsig(z) * (1.0f / 16.0f); pre[i] = run; }
;             seg_s[tq * 128 + k] = run;
;             __syncthreads();
;             float off = 0.f;
; #pragma unroll
;             for (int q = 0; q < 3; ++q) off += (q < tq) ? seg_s[q * 128 + k] : 0.f;
	v_fmac_f32_e32 v60, v34, v72
	v_fmac_f32_e32 v60, v35, v73
	v_fmac_f32_e32 v60, v32, v74
	v_fmac_f32_e32 v60, v33, v75
	v_min_f32_e32 v61, 0, v60
	v_mul_f32_e64 v60, |v60|, s36
	v_exp_f32_e32 v60, v60
	s_nop 0
	v_add_f32_e32 v60, 1.0, v60
	v_cmp_gt_f32_e32 vcc, s15, v60
	s_nop 1
	v_cndmask_b32_e64 v62, 0, 32, vcc
	v_ldexp_f32 v60, v60, v62
	v_log_f32_e32 v60, v60
	s_nop 0
	v_mul_f32_e32 v62, 0x3f317217, v60
	v_fma_f32 v62, v60, s16, -v62
	v_fmac_f32_e32 v62, 0x3377d1cf, v60
	v_fmac_f32_e32 v62, 0x3f317217, v60
	v_cmp_lt_f32_e64 s[54:55], |v60|, s17
	s_nop 1
	v_cndmask_b32_e64 v60, v60, v62, s[54:55]
	v_cndmask_b32_e32 v62, 0, v175, vcc
	v_sub_f32_e32 v60, v60, v62
	ds_read_b128 v[62:65], v123 offset:768
	ds_read_b128 v[66:69], v123 offset:784
	ds_read_b128 v[70:73], v123 offset:800
	ds_read_b128 v[74:77], v123 offset:816
	v_sub_f32_e32 v60, v61, v60
	s_waitcnt lgkmcnt(3)
	v_fma_f32 v61, v46, v62, v49
	v_fmac_f32_e32 v61, v47, v63
	v_fmac_f32_e32 v61, v44, v64
	v_fmac_f32_e32 v61, v45, v65
	s_waitcnt lgkmcnt(2)
	v_fmac_f32_e32 v61, v42, v66
	v_fmac_f32_e32 v61, v43, v67
	v_fmac_f32_e32 v61, v40, v68
	v_fmac_f32_e32 v61, v41, v69
	s_waitcnt lgkmcnt(1)
	v_fmac_f32_e32 v61, v38, v70
	v_fmac_f32_e32 v61, v39, v71
	v_fmac_f32_e32 v61, v36, v72
	v_fmac_f32_e32 v61, v37, v73
	s_waitcnt lgkmcnt(0)
	v_fmac_f32_e32 v61, v34, v74
	v_fmac_f32_e32 v61, v35, v75
	v_fmac_f32_e32 v61, v32, v76
	v_fmac_f32_e32 v61, v33, v77
	v_min_f32_e32 v62, 0, v61
	v_mul_f32_e64 v61, |v61|, s36
	v_exp_f32_e32 v61, v61
	v_fmamk_f32 v60, v60, 0x3d800000, v59
	v_add_f32_e32 v61, 1.0, v61
	v_cmp_gt_f32_e32 vcc, s15, v61
	s_nop 1
	v_cndmask_b32_e64 v63, 0, 32, vcc
	v_ldexp_f32 v61, v61, v63
	v_log_f32_e32 v61, v61
	s_nop 0
	v_mul_f32_e32 v63, 0x3f317217, v61
	v_fma_f32 v63, v61, s16, -v63
	v_fmac_f32_e32 v63, 0x3377d1cf, v61
	v_fmac_f32_e32 v63, 0x3f317217, v61
	v_cmp_lt_f32_e64 s[54:55], |v61|, s17
	s_nop 1
	v_cndmask_b32_e64 v61, v61, v63, s[54:55]
	v_cndmask_b32_e32 v63, 0, v175, vcc
	v_sub_f32_e32 v61, v61, v63
	v_sub_f32_e32 v61, v62, v61
	ds_read_b128 v[62:65], v123 offset:832
	ds_read_b128 v[66:69], v123 offset:848
	ds_read_b128 v[70:73], v123 offset:864
	ds_read_b128 v[74:77], v123 offset:880
	v_fmamk_f32 v61, v61, 0x3d800000, v60
	s_waitcnt lgkmcnt(3)
	v_fma_f32 v62, v46, v62, v49
	v_fmac_f32_e32 v62, v47, v63
	v_fmac_f32_e32 v62, v44, v64
	v_fmac_f32_e32 v62, v45, v65
	s_waitcnt lgkmcnt(2)
	v_fmac_f32_e32 v62, v42, v66
	v_fmac_f32_e32 v62, v43, v67
	v_fmac_f32_e32 v62, v40, v68
	v_fmac_f32_e32 v62, v41, v69
	s_waitcnt lgkmcnt(1)
	v_fmac_f32_e32 v62, v38, v70
	v_fmac_f32_e32 v62, v39, v71
	v_fmac_f32_e32 v62, v36, v72
	v_fmac_f32_e32 v62, v37, v73
	s_waitcnt lgkmcnt(0)
	v_fmac_f32_e32 v62, v34, v74
	v_fmac_f32_e32 v62, v35, v75
	v_fmac_f32_e32 v62, v32, v76
	v_fmac_f32_e32 v62, v33, v77
	v_min_f32_e32 v63, 0, v62
	v_mul_f32_e64 v62, |v62|, s36
	v_exp_f32_e32 v62, v62
	s_nop 0
	v_add_f32_e32 v62, 1.0, v62
	v_cmp_gt_f32_e32 vcc, s15, v62
	s_nop 1
	v_cndmask_b32_e64 v64, 0, 32, vcc
	v_ldexp_f32 v62, v62, v64
	v_log_f32_e32 v62, v62
	s_nop 0
	v_mul_f32_e32 v64, 0x3f317217, v62
	v_fma_f32 v64, v62, s16, -v64
	v_fmac_f32_e32 v64, 0x3377d1cf, v62
	v_fmac_f32_e32 v64, 0x3f317217, v62
	v_cmp_lt_f32_e64 s[54:55], |v62|, s17
	s_nop 1
	v_cndmask_b32_e64 v62, v62, v64, s[54:55]
	v_cndmask_b32_e32 v64, 0, v175, vcc
	v_sub_f32_e32 v62, v62, v64
	ds_read_b128 v[64:67], v123 offset:896
	ds_read_b128 v[68:71], v123 offset:912
	ds_read_b128 v[72:75], v123 offset:928
	ds_read_b128 v[76:79], v123 offset:944
	v_sub_f32_e32 v62, v63, v62
	s_waitcnt lgkmcnt(3)
	v_fma_f32 v63, v46, v64, v49
	v_fmac_f32_e32 v63, v47, v65
	v_fmac_f32_e32 v63, v44, v66
	v_fmac_f32_e32 v63, v45, v67
	s_waitcnt lgkmcnt(2)
	v_fmac_f32_e32 v63, v42, v68
	v_fmac_f32_e32 v63, v43, v69
	v_fmac_f32_e32 v63, v40, v70
	v_fmac_f32_e32 v63, v41, v71
	s_waitcnt lgkmcnt(1)
	v_fmac_f32_e32 v63, v38, v72
	v_fmac_f32_e32 v63, v39, v73
	v_fmac_f32_e32 v63, v36, v74
	v_fmac_f32_e32 v63, v37, v75
	s_waitcnt lgkmcnt(0)
	v_fmac_f32_e32 v63, v34, v76
	v_fmac_f32_e32 v63, v35, v77
	v_fmac_f32_e32 v63, v32, v78
	v_fmac_f32_e32 v63, v33, v79
	v_min_f32_e32 v64, 0, v63
	v_mul_f32_e64 v63, |v63|, s36
	v_exp_f32_e32 v63, v63
	v_fmamk_f32 v62, v62, 0x3d800000, v61
	v_add_f32_e32 v63, 1.0, v63
	v_cmp_gt_f32_e32 vcc, s15, v63
	s_nop 1
	v_cndmask_b32_e64 v65, 0, 32, vcc
	v_ldexp_f32 v63, v63, v65
	v_log_f32_e32 v63, v63
	s_nop 0
	v_mul_f32_e32 v65, 0x3f317217, v63
	v_fma_f32 v65, v63, s16, -v65
	v_fmac_f32_e32 v65, 0x3377d1cf, v63
	v_fmac_f32_e32 v65, 0x3f317217, v63
	v_cmp_lt_f32_e64 s[54:55], |v63|, s17
	s_nop 1
	v_cndmask_b32_e64 v63, v63, v65, s[54:55]
	v_cndmask_b32_e32 v65, 0, v175, vcc
	v_sub_f32_e32 v63, v63, v65
	v_sub_f32_e32 v63, v64, v63
	ds_read_b128 v[64:67], v123 offset:960
	ds_read_b128 v[68:71], v123 offset:976
	ds_read_b128 v[72:75], v123 offset:992
	ds_read_b128 v[76:79], v123 offset:1008
	v_fmamk_f32 v63, v63, 0x3d800000, v62
	s_waitcnt lgkmcnt(3)
	v_fmac_f32_e32 v49, v46, v64
	v_fmac_f32_e32 v49, v47, v65
	v_fmac_f32_e32 v49, v44, v66
	v_fmac_f32_e32 v49, v45, v67
	s_waitcnt lgkmcnt(2)
	v_fmac_f32_e32 v49, v42, v68
	v_fmac_f32_e32 v49, v43, v69
	v_fmac_f32_e32 v49, v40, v70
	v_fmac_f32_e32 v49, v41, v71
	s_waitcnt lgkmcnt(1)
	v_fmac_f32_e32 v49, v38, v72
	v_fmac_f32_e32 v49, v39, v73
	v_fmac_f32_e32 v49, v36, v74
	v_fmac_f32_e32 v49, v37, v75
	s_waitcnt lgkmcnt(0)
	v_fmac_f32_e32 v49, v34, v76
	v_fmac_f32_e32 v49, v35, v77
	v_fmac_f32_e32 v49, v32, v78
	v_fmac_f32_e32 v49, v33, v79
	v_mul_f32_e64 v33, |v49|, s36
	v_exp_f32_e32 v33, v33
	v_min_f32_e32 v32, 0, v49
	v_add_f32_e32 v33, 1.0, v33
	v_cmp_gt_f32_e32 vcc, s15, v33
	s_nop 1
	v_cndmask_b32_e64 v34, 0, 32, vcc
	v_ldexp_f32 v33, v33, v34
	v_log_f32_e32 v33, v33
	s_nop 0
	v_mul_f32_e32 v34, 0x3f317217, v33
	v_fma_f32 v34, v33, s16, -v34
	v_fmac_f32_e32 v34, 0x3377d1cf, v33
	v_fmac_f32_e32 v34, 0x3f317217, v33
	v_cmp_lt_f32_e64 s[54:55], |v33|, s17
	s_nop 1
	v_cndmask_b32_e64 v33, v33, v34, s[54:55]
	v_cndmask_b32_e32 v34, 0, v175, vcc
	v_sub_f32_e32 v33, v33, v34
	v_sub_f32_e32 v32, v32, v33
	v_fmamk_f32 v32, v32, 0x3d800000, v63
	v_mov_b32_e32 v33, 0
	v_mov_b32_e32 v34, 0
	ds_write_b32 v153, v32 offset:12800
	s_waitcnt lgkmcnt(0)
	s_barrier
	s_and_saveexec_b64 s[54:55], s[48:49]
	s_cbranch_execz .LBB0_429
	ds_read_b32 v34, v122 offset:12800
	s_waitcnt lgkmcnt(0)
	v_add_f32_e32 v34, 0, v34
	s_or_b64 exec, exec, s[54:55]
	v_mov_b32_e32 v35, 0
	s_and_saveexec_b64 s[54:55], s[50:51]
	s_cbranch_execnz .LBB0_430

; #define LAS __attribute__((address_space(3)))
; __device__ __forceinline__ void gla3_tile(const bf16* proj, const bf16* Sg, const float* BC, const float* gn  , bf16* Y,
;                                           LAS unsigned char* lds, int c, int hd, int tid_in) {
;     ...
;     const bf16* St = Sg + (size_t)(c * NH + hd) * HV * HK;
;     bf16x8 sfr[4][2]; u32x2 gpre[4][2];
; #pragma unroll
;     for (int ks = 0; ks < 4; ++ks)
; #pragma unroll
;         for (int nt = 0; nt < 2; ++nt) sfr[ks][nt] = *(const bf16x8*)(St + (size_t)(32 * wave + 16 * nt + fr) * HK + ks * 32 + fq * 8);
; #pragma unroll
;     for (int mt = 0; mt < 4; ++mt)
; #pragma unroll
;         for (int nt = 0; nt < 2; ++nt) gpre[mt][nt] = __builtin_nontemporal_load((const u32x2*)(proj + (row0 + 16 * mt + fr) * NIN + C_G + hd * HV + 32 * wave + 16 * nt + 4 * fq));
; #pragma unroll
;     for (int it = 0; it < 2; ++it) { const int ch = tid + NTHR * it, s = ch >> 4, k0 = (ch & 15) * 8;
;         const u32x4 qv = __builtin_nontemporal_load((const u32x4*)(proj + (row0 + s) * NIN + C_Q + hd * HK + k0)), kv = __builtin_nontemporal_load((const u32x4*)(proj + (row0 + s) * NIN + C_K + hd * HK + k0));
;         const f32x4 b0 = *(const f32x4*)(BC + (row0 + s) * DQK + hd * HK + k0), b1 = *(const f32x4*)(BC + (row0 + s) * DQK + hd * HK + k0 + 4);
;         u32x4 qe, qm, kd, km;
; #pragma unroll
;         for (int j = 0; j < 4; ++j) { const float ba = (j < 2) ? b0[2 * j] : b1[2 * j - 4], bb = (j < 2) ? b0[2 * j + 1] : b1[2 * j - 3];
;             const float ea = __expf(ba), eb = __expf(bb), ia = __expf(-ba), ib = __expf(-bb);
;             const float qa = bflo(qv[j]) * qscale, qb = bfhi(qv[j]) * qscale, ka = bflo(kv[j]), kb = bfhi(kv[j]);
;             qe[j] = pk2(qa * ea, qb * eb); qm[j] = pk2(qa * ia, qb * ib); kd[j] = pk2(ka * ia, kb * ib); km[j] = pk2(ka * ea, kb * eb); }
;         *(LAS u32x4*)(QE_s + s * QK_LD + k0) = qe; *(LAS u32x4*)(QM_s + s * QK_LD + k0) = qm; *(LAS u32x4*)(KD_s + s * QK_LD + k0) = kd; *(LAS u32x4*)(KM_s + s * QK_LD + k0) = km; }
; #pragma unroll
;     for (int it = 0; it < 2; ++it) { const int item = tid + NTHR * it, s0 = (item & 31) * 2, v0 = (item >> 5) * 8;
;         const u32x4 va = *(const u32x4*)(proj + (row0 + s0) * NIN + C_V + hd * HV + v0), vb = *(const u32x4*)(proj + (row0 + s0 + 1) * NIN + C_V + hd * HV + v0);
.LBB0_553:
	s_bfe_u32 s3, s24, 0x80002
	s_and_b32 s20, s24, 3
	s_lshl_b32 s2, s3, 6
	s_lshl_b32 s4, s20, 16
	s_lshl_b32 s3, s3, 18
	v_mov_b32_e32 v78, v168
	s_or_b32 s3, s3, s4
	v_readlane_b32 s4, v249, 2
	v_readlane_b32 s5, v249, 3
	v_bfe_u32 v79, v78, 4, 2
	s_add_u32 s4, s4, s3
	v_and_b32_e32 v71, 15, v78
	s_addc_u32 s5, s5, 0
	v_lshlrev_b32_e32 v66, 4, v79
	v_mov_b32_e32 v67, v137
	v_lshl_add_u64 v[4:5], s[4:5], 0, v[66:67]
	v_or_b32_e32 v67, s2, v71
	v_mul_u32_u24_e32 v36, 0x1900, v67
	v_ashrrev_i32_e32 v80, 6, v78
	v_lshlrev_b32_e32 v36, 1, v36
	v_mov_b32_e32 v37, v137
	v_lshlrev_b32_e32 v64, 5, v80
	v_lshl_add_u64 v[36:37], s[92:93], 0, v[36:37]
	s_lshl_b32 s4, s20, 9
	s_mov_b32 s5, s87
	v_or_b32_e32 v68, v64, v71
	v_ashrrev_i32_e32 v65, 31, v64
	v_lshl_add_u64 v[36:37], v[36:37], 0, s[4:5]
	v_lshlrev_b32_e32 v136, 3, v79
	s_waitcnt vmcnt(21)
	v_or_b32_e32 v8, 16, v68
	v_lshl_add_u64 v[36:37], v[64:65], 1, v[36:37]
	v_ashrrev_i32_e32 v69, 31, v68
	v_ashrrev_i32_e32 v9, 31, v8
	v_lshl_add_u64 v[36:37], v[36:37], 0, v[136:137]
	s_movk_i32 s3, 0x2000
	v_lshlrev_b64 v[6:7], 8, v[68:69]
	v_lshlrev_b64 v[8:9], 8, v[8:9]
	v_add_co_u32_e32 v40, vcc, s3, v36
	v_lshl_add_u64 v[6:7], v[4:5], 0, v[6:7]
	v_lshl_add_u64 v[8:9], v[4:5], 0, v[8:9]
	s_mov_b64 s[26:27], 0x2800
	v_addc_co_u32_e32 v41, vcc, 0, v37, vcc
	s_mov_b32 s3, 0x34000
	global_load_dwordx4 v[28:31], v[6:7], off
	global_load_dwordx4 v[32:35], v[8:9], off
	global_load_dwordx4 v[20:23], v[6:7], off offset:64
	global_load_dwordx4 v[24:27], v[8:9], off offset:64
	global_load_dwordx4 v[12:15], v[6:7], off offset:128
	global_load_dwordx4 v[16:19], v[8:9], off offset:128
	s_nop 0
	global_load_dwordx4 v[4:7], v[6:7], off offset:192
	s_nop 0
	global_load_dwordx4 v[8:11], v[8:9], off offset:192
	v_lshl_add_u64 v[38:39], v[36:37], 0, s[26:27]
	global_load_dwordx2 v[62:63], v[40:41], off offset:2048 nt
	global_load_dwordx2 v[60:61], v[38:39], off offset:32 nt
	v_add_co_u32_e32 v40, vcc, s3, v36
	s_mov_b64 s[26:27], 0x34800
	s_nop 0
	v_addc_co_u32_e32 v41, vcc, 0, v37, vcc
	s_mov_b32 s3, 0x66000
	v_lshl_add_u64 v[38:39], v[36:37], 0, s[26:27]
	global_load_dwordx2 v[58:59], v[40:41], off offset:2048 nt
	global_load_dwordx2 v[56:57], v[38:39], off offset:32 nt
	s_mov_b64 s[26:27], 0x66800
	v_add_co_u32_e32 v40, vcc, s3, v36
	v_lshl_add_u64 v[38:39], v[36:37], 0, s[26:27]
	s_nop 0
	v_addc_co_u32_e32 v41, vcc, 0, v37, vcc
	s_mov_b64 s[26:27], 0x98800
	s_mov_b32 s3, 0x98000
	global_load_dwordx2 v[54:55], v[40:41], off offset:2048 nt
	global_load_dwordx2 v[52:53], v[38:39], off offset:32 nt
	v_lshl_add_u64 v[38:39], v[36:37], 0, s[26:27]
	v_add_co_u32_e32 v36, vcc, s3, v36
	s_lshl_b32 s86, s20, 8
	s_nop 0
	v_addc_co_u32_e32 v37, vcc, 0, v37, vcc
	global_load_dwordx2 v[50:51], v[36:37], off offset:2048 nt
	global_load_dwordx2 v[48:49], v[38:39], off offset:32 nt
	v_lshlrev_b32_e32 v36, 3, v78
	v_ashrrev_i32_e32 v76, 4, v78
	s_mov_b32 s3, s87
	v_and_b32_e32 v36, 0x78, v36
	s_add_u32 s26, s50, s4
	v_ashrrev_i32_e32 v77, 31, v76
	s_addc_u32 s27, s51, 0
	v_lshlrev_b32_e32 v136, 2, v36
	v_lshl_add_u64 v[44:45], v[76:77], 0, s[2:3]
	v_mov_b64_e32 v[74:75], s[92:93]
	v_lshl_add_u64 v[72:73], s[26:27], 0, v[136:137]
	v_lshlrev_b32_e32 v136, 1, v36
	v_mad_i64_i32 v[36:37], s[26:27], v44, s22, v[74:75]
	v_lshl_add_u64 v[36:37], v[36:37], 0, s[86:87]
	v_lshl_add_u64 v[36:37], v[36:37], 0, v[136:137]
	s_movk_i32 s20, 0x1000
	v_add_co_u32_e32 v36, vcc, s20, v36
	v_lshlrev_b64 v[44:45], 11, v[44:45]
	s_nop 0
	v_addc_co_u32_e32 v37, vcc, 0, v37, vcc
	v_lshl_add_u64 v[82:83], v[72:73], 0, v[44:45]
	s_mov_b64 s[100:101], 0x64000
	v_lshl_add_u64 v[240:241], v[36:37], 0, s[100:101]
	s_mov_b64 s[100:101], 0x10000
	v_lshl_add_u64 v[242:243], v[82:83], 0, s[100:101]
	global_load_dwordx4 v[40:43], v[36:37], off offset:2048 nt
	s_nop 0
	global_load_dwordx4 v[36:39], v[36:37], off offset:3072 nt
	s_nop 0
	global_load_dwordx4 v[44:47], v[82:83], off offset:16
	s_nop 0
	global_load_dwordx4 v[82:85], v[82:83], off
	global_load_dwordx4 v[208:211], v[240:241], off offset:2048 nt
	global_load_dwordx4 v[212:215], v[240:241], off offset:3072 nt
	global_load_dwordx4 v[216:219], v[242:243], off offset:16
	global_load_dwordx4 v[220:223], v[242:243], off
	v_lshlrev_b32_e32 v244, 1, v78
	v_and_b32_e32 v244, 62, v244
	v_or_b32_e32 v244, s2, v244
	v_mul_u32_u24_e32 v240, 0x3200, v244
	v_mov_b32_e32 v241, 0
	v_lshl_add_u64 v[240:241], s[92:93], 0, v[240:241]
	v_lshl_add_u64 v[240:241], v[240:241], 0, s[4:5]
	v_ashrrev_i32_e32 v244, 2, v78
	v_and_b32_e32 v244, -8, v244
	v_ashrrev_i32_e32 v245, 31, v244
	v_lshlrev_b64 v[244:245], 1, v[244:245]
	v_lshl_add_u64 v[240:241], v[240:241], 0, v[244:245]
	s_mov_b64 s[100:101], 0x2000
	v_lshl_add_u64 v[242:243], v[240:241], 0, s[100:101]
	s_mov_b64 s[100:101], 0x5200
	v_lshl_add_u64 v[240:241], v[240:241], 0, s[100:101]
	global_load_dwordx4 v[224:227], v[242:243], off
	global_load_dwordx4 v[228:231], v[240:241], off
	global_load_dwordx4 v[232:235], v[242:243], off offset:256
	global_load_dwordx4 v[236:239], v[240:241], off offset:256
	v_add_u32_e32 v70, 0, v136
	s_movk_i32 s25, 0x110
	s_waitcnt vmcnt(10)
	v_and_b32_e32 v86, 0xffff0000, v36
	s_waitcnt vmcnt(8)
; #define LAS __attribute__((address_space(3)))
; __device__ __forceinline__ float bflo(unsigned u) { return __uint_as_float(u << 16); }
; __device__ __forceinline__ float bfhi(unsigned u) { return __uint_as_float(u & 0xffff0000u); }
; __device__ __forceinline__ unsigned pk2(float lo, float hi) { return pg8::cvt_pk_bf16(lo, hi); }
; __device__ __forceinline__ void gla3_tile(const bf16* proj, const bf16* Sg, const float* BC, const float* gn  , bf16* Y,
;                                           LAS unsigned char* lds, int c, int hd, int tid_in) {
;     ...
;     for (int it = 0; it < 2; ++it) { const int ch = tid + NTHR * it, s = ch >> 4, k0 = (ch & 15) * 8;
;         const u32x4 qv = __builtin_nontemporal_load((const u32x4*)(proj + (row0 + s) * NIN + C_Q + hd * HK + k0)), kv = __builtin_nontemporal_load((const u32x4*)(proj + (row0 + s) * NIN + C_K + hd * HK + k0));
;         const f32x4 b0 = *(const f32x4*)(BC + (row0 + s) * DQK + hd * HK + k0), b1 = *(const f32x4*)(BC + (row0 + s) * DQK + hd * HK + k0 + 4);
;         u32x4 qe, qm, kd, km;
; #pragma unroll
;         for (int j = 0; j < 4; ++j) { const float ba = (j < 2) ? b0[2 * j] : b1[2 * j - 4], bb = (j < 2) ? b0[2 * j + 1] : b1[2 * j - 3];
;             const float ea = __expf(ba), eb = __expf(bb), ia = __expf(-ba), ib = __expf(-bb);
;             const float qa = bflo(qv[j]) * qscale, qb = bfhi(qv[j]) * qscale, ka = bflo(kv[j]), kb = bfhi(kv[j]);
;             qe[j] = pk2(qa * ea, qb * eb); qm[j] = pk2(qa * ia, qb * ib); kd[j] = pk2(ka * ia, kb * ib); km[j] = pk2(ka * ea, kb * eb); }
;         *(LAS u32x4*)(QE_s + s * QK_LD + k0) = qe; *(LAS u32x4*)(QM_s + s * QK_LD + k0) = qm; *(LAS u32x4*)(KD_s + s * QK_LD + k0) = kd; *(LAS u32x4*)(KM_s + s * QK_LD + k0) = km; }
	v_mul_f32_e32 v65, 0x3fb8aa3b, v82
	v_mul_f32_e32 v69, 0x3fb8aa3b, v83
	v_mul_f32_e32 v77, 0xbfb8aa3b, v82
	v_mul_f32_e32 v81, 0xbfb8aa3b, v83
	v_exp_f32_e32 v65, v65
	v_exp_f32_e32 v69, v69
	v_exp_f32_e32 v77, v77
	v_exp_f32_e32 v81, v81
	v_lshlrev_b32_e32 v82, 16, v40
	v_and_b32_e32 v40, 0xffff0000, v40
	v_mul_f32_e32 v82, 0x3db504f3, v82
	v_mul_f32_e32 v40, 0x3db504f3, v40
	v_lshlrev_b32_e32 v83, 16, v36
	v_mul_f32_e32 v36, v82, v65
	v_mul_f32_e32 v87, v40, v69
	v_mul_f32_e32 v82, v82, v77
	v_mul_f32_e32 v40, v40, v81
	v_mul_f32_e32 v77, v77, v83
	v_mul_f32_e32 v81, v81, v86
	v_mul_f32_e32 v65, v65, v83
	v_mul_f32_e32 v69, v69, v86
	v_cvt_pk_bf16_f32 v36, v36, v87
	v_cvt_pk_bf16_f32 v40, v82, v40
	v_cvt_pk_bf16_f32 v82, v77, v81
	v_cvt_pk_bf16_f32 v86, v65, v69
	v_mul_f32_e32 v65, 0x3fb8aa3b, v84
	v_mul_f32_e32 v69, 0x3fb8aa3b, v85
	v_mul_f32_e32 v77, 0xbfb8aa3b, v84
	v_mul_f32_e32 v81, 0xbfb8aa3b, v85
	v_exp_f32_e32 v65, v65
	v_exp_f32_e32 v69, v69
	v_exp_f32_e32 v77, v77
	v_exp_f32_e32 v81, v81
	v_lshlrev_b32_e32 v83, 16, v41
	v_and_b32_e32 v41, 0xffff0000, v41
	v_mul_f32_e32 v83, 0x3db504f3, v83
	v_mul_f32_e32 v41, 0x3db504f3, v41
	v_lshlrev_b32_e32 v84, 16, v37
	v_and_b32_e32 v85, 0xffff0000, v37
	v_mul_f32_e32 v37, v83, v65
	v_mul_f32_e32 v87, v41, v69
	v_mul_f32_e32 v83, v83, v77
	v_mul_f32_e32 v41, v41, v81
	v_mul_f32_e32 v65, v65, v84
	v_mul_f32_e32 v69, v69, v85
	v_cvt_pk_bf16_f32 v37, v37, v87
	v_cvt_pk_bf16_f32 v41, v83, v41
	v_mul_f32_e32 v77, v77, v84
	v_mul_f32_e32 v81, v81, v85
	v_cvt_pk_bf16_f32 v83, v77, v81
	v_cvt_pk_bf16_f32 v87, v65, v69
	v_mul_f32_e32 v65, 0x3fb8aa3b, v44
	v_mul_f32_e32 v69, 0x3fb8aa3b, v45
	v_mul_f32_e32 v44, 0xbfb8aa3b, v44
	v_mul_f32_e32 v45, 0xbfb8aa3b, v45
	v_exp_f32_e32 v65, v65
	v_exp_f32_e32 v69, v69
	v_exp_f32_e32 v44, v44
	v_exp_f32_e32 v45, v45
	v_lshlrev_b32_e32 v77, 16, v42
	v_and_b32_e32 v42, 0xffff0000, v42
	v_mul_f32_e32 v77, 0x3db504f3, v77
	v_mul_f32_e32 v42, 0x3db504f3, v42
	v_lshlrev_b32_e32 v81, 16, v38
	v_and_b32_e32 v85, 0xffff0000, v38
	v_mul_f32_e32 v38, v77, v65
	v_mul_f32_e32 v84, v42, v69
	v_mul_f32_e32 v77, v77, v44
	v_mul_f32_e32 v42, v42, v45
	v_mul_f32_e32 v44, v44, v81
	v_mul_f32_e32 v45, v45, v85
	v_cvt_pk_bf16_f32 v38, v38, v84
	v_cvt_pk_bf16_f32 v42, v77, v42
	v_cvt_pk_bf16_f32 v84, v44, v45
	v_mul_f32_e32 v44, v65, v81
	v_mul_f32_e32 v45, v69, v85
	v_cvt_pk_bf16_f32 v88, v44, v45
	v_mul_f32_e32 v44, 0x3fb8aa3b, v46
	v_mul_f32_e32 v45, 0x3fb8aa3b, v47
	v_mul_f32_e32 v46, 0xbfb8aa3b, v46
	v_mul_f32_e32 v47, 0xbfb8aa3b, v47
	v_exp_f32_e32 v44, v44
	v_exp_f32_e32 v45, v45
	v_exp_f32_e32 v46, v46
	v_exp_f32_e32 v47, v47
	v_lshlrev_b32_e32 v65, 16, v43
	v_and_b32_e32 v43, 0xffff0000, v43
	v_mul_f32_e32 v65, 0x3db504f3, v65
	v_mul_f32_e32 v43, 0x3db504f3, v43
	v_lshlrev_b32_e32 v69, 16, v39
	v_and_b32_e32 v77, 0xffff0000, v39
	v_mul_f32_e32 v39, v65, v44
	v_mul_f32_e32 v81, v43, v45
	v_mul_f32_e32 v65, v65, v46
	v_mul_f32_e32 v43, v43, v47
	v_cvt_pk_bf16_f32 v39, v39, v81
	v_cvt_pk_bf16_f32 v43, v65, v43
	v_mul_f32_e32 v44, v44, v69
	v_mul_f32_e32 v45, v45, v77
	v_add_u32_e32 v65, 0x200, v78
	v_mul_f32_e32 v46, v46, v69
	v_mul_f32_e32 v47, v47, v77
	v_cvt_pk_bf16_f32 v85, v46, v47
	v_cvt_pk_bf16_f32 v89, v44, v45
	v_mad_u64_u32 v[44:45], s[26:27], v76, s25, v[70:71]
	v_ashrrev_i32_e32 v76, 4, v65
	v_ashrrev_i32_e32 v77, 31, v76
	ds_write_b128 v44, v[36:39]
	ds_write_b128 v44, v[40:43] offset:17408
	ds_write_b128 v44, v[82:85] offset:34816
	ds_write_b128 v44, v[86:89] offset:52224
	v_lshl_add_u64 v[44:45], v[76:77], 0, s[2:3]
	v_mad_i64_i32 v[36:37], s[26:27], v44, s22, v[74:75]
	v_lshl_add_u64 v[36:37], v[36:37], 0, s[86:87]
	v_lshl_add_u64 v[36:37], v[36:37], 0, v[136:137]
	v_add_co_u32_e32 v40, vcc, s20, v36
	v_lshlrev_b64 v[44:45], 11, v[44:45]
	s_nop 0
	v_addc_co_u32_e32 v41, vcc, 0, v37, vcc
	v_lshl_add_u64 v[72:73], v[72:73], 0, v[44:45]
	s_waitcnt vmcnt(4)
	v_mov_b32_e32 v36, v208
	v_mov_b32_e32 v37, v209
	v_mov_b32_e32 v38, v210
	v_mov_b32_e32 v39, v211
	s_nop 0
	v_mov_b32_e32 v40, v212
	v_mov_b32_e32 v41, v213
	v_mov_b32_e32 v42, v214
	v_mov_b32_e32 v43, v215
	s_nop 0
	v_mov_b32_e32 v44, v216
	v_mov_b32_e32 v45, v217
	v_mov_b32_e32 v46, v218
	v_mov_b32_e32 v47, v219
	s_nop 0
	v_mov_b32_e32 v72, v220
	v_mov_b32_e32 v73, v221
	v_mov_b32_e32 v74, v222
	v_mov_b32_e32 v75, v223
	v_readlane_b32 s3, v247, 31
	s_movk_i32 s20, 0x110
	s_waitcnt vmcnt(4)
	v_lshlrev_b32_e32 v81, 16, v36
	v_and_b32_e32 v36, 0xffff0000, v36
	s_waitcnt vmcnt(4)
; #define LAS __attribute__((address_space(3)))
; __device__ __forceinline__ float bflo(unsigned u) { return __uint_as_float(u << 16); }
; __device__ __forceinline__ float bfhi(unsigned u) { return __uint_as_float(u & 0xffff0000u); }
; __device__ __forceinline__ unsigned pk2(float lo, float hi) { return pg8::cvt_pk_bf16(lo, hi); }
; __device__ __forceinline__ void gla3_tile(const bf16* proj, const bf16* Sg, const float* BC, const float* gn  , bf16* Y,
;                                           LAS unsigned char* lds, int c, int hd, int tid_in) {
;     ...
;         for (int j = 0; j < 4; ++j) { const float ba = (j < 2) ? b0[2 * j] : b1[2 * j - 4], bb = (j < 2) ? b0[2 * j + 1] : b1[2 * j - 3];
;             const float ea = __expf(ba), eb = __expf(bb), ia = __expf(-ba), ib = __expf(-bb);
;             const float qa = bflo(qv[j]) * qscale, qb = bfhi(qv[j]) * qscale, ka = bflo(kv[j]), kb = bfhi(kv[j]);
;             qe[j] = pk2(qa * ea, qb * eb); qm[j] = pk2(qa * ia, qb * ib); kd[j] = pk2(ka * ia, kb * ib); km[j] = pk2(ka * ea, kb * eb); }
;         *(LAS u32x4*)(QE_s + s * QK_LD + k0) = qe; *(LAS u32x4*)(QM_s + s * QK_LD + k0) = qm; *(LAS u32x4*)(KD_s + s * QK_LD + k0) = kd; *(LAS u32x4*)(KM_s + s * QK_LD + k0) = km; }
; #pragma unroll
;     for (int it = 0; it < 2; ++it) { const int item = tid + NTHR * it, s0 = (item & 31) * 2, v0 = (item >> 5) * 8;
;         const u32x4 va = *(const u32x4*)(proj + (row0 + s0) * NIN + C_V + hd * HV + v0), vb = *(const u32x4*)(proj + (row0 + s0 + 1) * NIN + C_V + hd * HV + v0);
; #pragma unroll
;         for (int p = 0; p < 4; ++p) { *(LAS unsigned*)(vT_s + (v0 + 2 * p) * TR_LD + s0) = (va[p] & 0xffffu) | (vb[p] << 16);
;             *(LAS unsigned*)(vT_s + (v0 + 2 * p + 1) * TR_LD + s0) = (va[p] >> 16) | (vb[p] & 0xffff0000u); } }
;     __syncthreads();
; #pragma unroll
;     for (int pi = 0; pi < 2; ++pi) { const int p = wave + 8 * pi, tt = p >> 2, st = p & 3;
;         f32x4 lo = (f32x4){0.f, 0.f, 0.f, 0.f}, hi = (f32x4){0.f, 0.f, 0.f, 0.f};
;         if (st <= tt) {
	v_mul_f32_e32 v69, 0x3fb8aa3b, v72
	v_mul_f32_e32 v77, 0x3fb8aa3b, v73
	v_exp_f32_e32 v69, v69
	v_exp_f32_e32 v77, v77
	v_mul_f32_e32 v72, 0xbfb8aa3b, v72
	v_mul_f32_e32 v73, 0xbfb8aa3b, v73
	v_exp_f32_e32 v72, v72
	v_exp_f32_e32 v73, v73
	v_mul_f32_e32 v81, 0x3db504f3, v81
	v_mul_f32_e32 v82, 0x3db504f3, v36
	v_lshlrev_b32_e32 v83, 16, v40
	v_and_b32_e32 v84, 0xffff0000, v40
	v_mul_f32_e32 v36, v81, v69
	v_mul_f32_e32 v40, v82, v77
	v_cvt_pk_bf16_f32 v36, v36, v40
	v_mul_f32_e32 v40, v81, v72
	v_mul_f32_e32 v81, v82, v73
	v_mul_f32_e32 v72, v72, v83
	v_mul_f32_e32 v73, v73, v84
	v_cvt_pk_bf16_f32 v40, v40, v81
	v_cvt_pk_bf16_f32 v72, v72, v73
	v_mul_f32_e32 v69, v69, v83
	v_mul_f32_e32 v73, v77, v84
	v_cvt_pk_bf16_f32 v82, v69, v73
	v_mul_f32_e32 v69, 0x3fb8aa3b, v74
	v_mul_f32_e32 v73, 0x3fb8aa3b, v75
	v_exp_f32_e32 v69, v69
	v_exp_f32_e32 v77, v73
	v_mul_f32_e32 v73, 0xbfb8aa3b, v74
	v_mul_f32_e32 v74, 0xbfb8aa3b, v75
	v_exp_f32_e32 v73, v73
	v_exp_f32_e32 v74, v74
	v_lshlrev_b32_e32 v75, 16, v37
	v_and_b32_e32 v37, 0xffff0000, v37
	v_mul_f32_e32 v75, 0x3db504f3, v75
	v_mul_f32_e32 v81, 0x3db504f3, v37
	v_lshlrev_b32_e32 v83, 16, v41
	v_and_b32_e32 v84, 0xffff0000, v41
	v_mul_f32_e32 v37, v75, v69
	v_mul_f32_e32 v41, v81, v77
	v_cvt_pk_bf16_f32 v37, v37, v41
	v_mul_f32_e32 v41, v75, v73
	v_mul_f32_e32 v75, v81, v74
	v_mul_f32_e32 v73, v73, v83
	v_mul_f32_e32 v74, v74, v84
	v_cvt_pk_bf16_f32 v41, v41, v75
	v_cvt_pk_bf16_f32 v73, v73, v74
	v_mul_f32_e32 v69, v69, v83
	v_mul_f32_e32 v74, v77, v84
	v_cvt_pk_bf16_f32 v83, v69, v74
	v_mul_f32_e32 v69, 0x3fb8aa3b, v44
	v_mul_f32_e32 v74, 0x3fb8aa3b, v45
	v_exp_f32_e32 v69, v69
	v_exp_f32_e32 v75, v74
	v_mul_f32_e32 v44, 0xbfb8aa3b, v44
	v_mul_f32_e32 v45, 0xbfb8aa3b, v45
	v_exp_f32_e32 v44, v44
	v_exp_f32_e32 v45, v45
	v_lshlrev_b32_e32 v74, 16, v38
	v_and_b32_e32 v38, 0xffff0000, v38
	v_mul_f32_e32 v74, 0x3db504f3, v74
	v_mul_f32_e32 v77, 0x3db504f3, v38
	v_lshlrev_b32_e32 v81, 16, v42
	v_and_b32_e32 v84, 0xffff0000, v42
	v_mul_f32_e32 v38, v74, v69
	v_mul_f32_e32 v42, v77, v75
	v_cvt_pk_bf16_f32 v38, v38, v42
	v_mul_f32_e32 v42, v74, v44
	v_mul_f32_e32 v74, v77, v45
	v_mul_f32_e32 v44, v44, v81
	v_mul_f32_e32 v45, v45, v84
	v_cvt_pk_bf16_f32 v42, v42, v74
	v_cvt_pk_bf16_f32 v74, v44, v45
	v_mul_f32_e32 v44, v69, v81
	v_mul_f32_e32 v45, v75, v84
	v_cvt_pk_bf16_f32 v84, v44, v45
	v_mul_f32_e32 v44, 0x3fb8aa3b, v46
	v_mul_f32_e32 v45, 0x3fb8aa3b, v47
	v_exp_f32_e32 v44, v44
	v_exp_f32_e32 v45, v45
	v_mul_f32_e32 v46, 0xbfb8aa3b, v46
	v_exp_f32_e32 v46, v46
	v_mul_f32_e32 v47, 0xbfb8aa3b, v47
	v_exp_f32_e32 v47, v47
	v_lshlrev_b32_e32 v69, 16, v39
	v_and_b32_e32 v39, 0xffff0000, v39
	v_mul_f32_e32 v69, 0x3db504f3, v69
	v_mul_f32_e32 v75, 0x3db504f3, v39
	v_lshlrev_b32_e32 v77, 16, v43
	v_and_b32_e32 v81, 0xffff0000, v43
	v_mul_f32_e32 v39, v69, v44
	v_mul_f32_e32 v43, v75, v45
	v_cvt_pk_bf16_f32 v39, v39, v43
	v_mul_f32_e32 v43, v69, v46
	v_mul_f32_e32 v44, v44, v77
	v_mul_f32_e32 v45, v45, v81
	v_mul_f32_e32 v69, v75, v47
	v_cvt_pk_bf16_f32 v43, v43, v69
	v_mul_f32_e32 v46, v46, v77
	v_mul_f32_e32 v47, v47, v81
	v_cvt_pk_bf16_f32 v75, v46, v47
	v_cvt_pk_bf16_f32 v85, v44, v45
	v_mad_u64_u32 v[44:45], s[26:27], v76, s25, v[70:71]
	ds_write_b128 v44, v[36:39]
	ds_write_b128 v44, v[40:43] offset:17408
	ds_write_b128 v44, v[72:75] offset:34816
	ds_write_b128 v44, v[82:85] offset:52224
	v_lshlrev_b32_e32 v36, 1, v78
	v_and_b32_e32 v69, 62, v36
	v_or_b32_e32 v36, s2, v69
	v_mul_u32_u24_e32 v136, 0x3200, v36
	v_lshl_add_u64 v[36:37], s[92:93], 0, v[136:137]
	v_lshl_add_u64 v[36:37], v[36:37], 0, s[4:5]
	s_mov_b64 s[4:5], 0x2000
	v_lshl_add_u64 v[44:45], v[36:37], 0, s[4:5]
	s_mov_b64 s[4:5], 0x5200
	v_lshl_add_u64 v[46:47], v[36:37], 0, s[4:5]
	v_ashrrev_i32_e32 v36, 2, v78
	v_and_b32_e32 v72, -8, v36
	v_ashrrev_i32_e32 v73, 31, v72
	v_lshlrev_b64 v[40:41], 1, v[72:73]
	v_lshl_add_u64 v[36:37], v[44:45], 0, v[40:41]
	s_waitcnt vmcnt(2)
	v_mov_b32_e32 v36, v224
	v_mov_b32_e32 v37, v225
	v_mov_b32_e32 v38, v226
	v_mov_b32_e32 v39, v227
	v_lshl_add_u64 v[40:41], v[46:47], 0, v[40:41]
	v_mov_b32_e32 v40, v228
	v_mov_b32_e32 v41, v229
	v_mov_b32_e32 v42, v230
	v_mov_b32_e32 v43, v231
	v_mul_lo_u32 v72, v72, s37
	v_lshlrev_b32_e32 v69, 1, v69
	v_add3_u32 v72, s3, v72, v69
	s_waitcnt vmcnt(2)
	v_and_b32_e32 v70, 0xffff, v36
	v_lshrrev_b32_e32 v36, 16, v36
	s_waitcnt vmcnt(2)
	v_lshl_or_b32 v70, v40, 16, v70
	v_and_or_b32 v36, v40, s14, v36
	ds_write2_b32 v72, v70, v36 offset1:36
	v_and_b32_e32 v36, 0xffff, v37
	v_lshrrev_b32_e32 v37, 16, v37
	v_lshl_or_b32 v36, v41, 16, v36
	v_and_or_b32 v37, v41, s14, v37
	ds_write2_b32 v72, v36, v37 offset0:72 offset1:108
	v_and_b32_e32 v36, 0xffff, v38
	v_lshrrev_b32_e32 v37, 16, v38
	v_lshl_or_b32 v36, v42, 16, v36
	v_and_or_b32 v37, v42, s14, v37
	ds_write2_b32 v72, v36, v37 offset0:144 offset1:180
	v_and_b32_e32 v36, 0xffff, v39
	v_lshrrev_b32_e32 v37, 16, v39
	v_lshl_or_b32 v36, v43, 16, v36
	v_and_or_b32 v37, v43, s14, v37
	ds_write2_b32 v72, v36, v37 offset0:216 offset1:252
	v_ashrrev_i32_e32 v36, 2, v65
	v_and_b32_e32 v72, -8, v36
	v_ashrrev_i32_e32 v73, 31, v72
	v_lshlrev_b64 v[40:41], 1, v[72:73]
	v_lshl_add_u64 v[36:37], v[44:45], 0, v[40:41]
	s_waitcnt vmcnt(0)
	v_mov_b32_e32 v36, v232
	v_mov_b32_e32 v37, v233
	v_mov_b32_e32 v38, v234
	v_mov_b32_e32 v39, v235
	v_lshl_add_u64 v[40:41], v[46:47], 0, v[40:41]
	v_mov_b32_e32 v40, v236
	v_mov_b32_e32 v41, v237
	v_mov_b32_e32 v42, v238
	v_mov_b32_e32 v43, v239
	v_mul_lo_u32 v45, v72, s37
	v_add3_u32 v45, s3, v45, v69
	v_and_b32_e32 v65, 3, v80
	v_lshlrev_b32_e32 v46, 4, v65
	s_waitcnt vmcnt(1)
	v_and_b32_e32 v44, 0xffff, v36
	v_lshrrev_b32_e32 v36, 16, v36
	s_waitcnt vmcnt(0)
	v_lshl_or_b32 v44, v40, 16, v44
	v_and_or_b32 v36, v40, s14, v36
	ds_write2_b32 v45, v44, v36 offset1:36
	v_and_b32_e32 v36, 0xffff, v37
	v_lshrrev_b32_e32 v37, 16, v37
	v_lshl_or_b32 v36, v41, 16, v36
	v_and_or_b32 v37, v41, s14, v37
	ds_write2_b32 v45, v36, v37 offset0:72 offset1:108
	v_and_b32_e32 v36, 0xffff, v38
	v_lshrrev_b32_e32 v37, 16, v38
	v_lshl_or_b32 v36, v42, 16, v36
	v_and_or_b32 v37, v42, s14, v37
	ds_write2_b32 v45, v36, v37 offset0:144 offset1:180
	v_and_b32_e32 v36, 0xffff, v39
	v_lshrrev_b32_e32 v37, 16, v39
	v_lshl_or_b32 v36, v43, 16, v36
	v_and_or_b32 v37, v43, s14, v37
	ds_write2_b32 v45, v36, v37 offset0:216 offset1:252
	v_or_b32_e32 v36, v46, v71
	v_add_u32_e32 v44, 0, v66
	v_ashrrev_i32_e32 v37, 8, v78
	v_mad_u32_u24 v47, v36, s25, v44
	v_cmp_le_i32_e32 vcc, v65, v37
	v_lshl_or_b32 v72, v37, 4, v71
	v_mov_b32_e32 v36, 0
	v_mov_b32_e32 v40, 0
	v_mov_b32_e32 v41, 0
	v_mov_b32_e32 v42, 0
	v_mov_b32_e32 v43, 0
	s_waitcnt lgkmcnt(0)
	s_barrier
; #define LAS __attribute__((address_space(3)))
; __device__ __forceinline__ void gla3_tile(const bf16* proj, const bf16* Sg, const float* BC, const float* gn  , bf16* Y,
;                                           LAS unsigned char* lds, int c, int hd, int tid_in) {
;     ...
;         if (st <= tt) {
; #pragma unroll
;             for (int ks = 0; ks < 4; ++ks) { const bf16x8 a = *(const LAS bf16x8*)(KD_s + (16 * st + fr) * QK_LD + ks * 32 + fq * 8), b = *(const LAS bf16x8*)(QE_s + (16 * tt + fr) * QK_LD + ks * 32 + fq * 8);
;                 lo = __builtin_amdgcn_mfma_f32_16x16x32_bf16(a, b, lo, 0, 0, 0); } }
	s_and_saveexec_b64 s[4:5], vcc
	s_cbranch_execz .LBB0_555
	v_mad_u64_u32 v[42:43], s[26:27], v72, s20, v[44:45]
	ds_read_b128 v[38:41], v47 offset:34816
	ds_read_b128 v[74:77], v42
	s_waitcnt lgkmcnt(0)
	v_mfma_f32_16x16x32_bf16 v[38:41], v[38:41], v[74:77], 0
	ds_read_b128 v[74:77], v47 offset:34880
	ds_read_b128 v[82:85], v42 offset:64
	s_waitcnt lgkmcnt(0)
	v_mfma_f32_16x16x32_bf16 v[38:41], v[74:77], v[82:85], v[38:41]
	ds_read_b128 v[74:77], v47 offset:34944
	ds_read_b128 v[82:85], v42 offset:128
	s_waitcnt lgkmcnt(0)
	v_mfma_f32_16x16x32_bf16 v[38:41], v[74:77], v[82:85], v[38:41]
	ds_read_b128 v[74:77], v47 offset:35008
	ds_read_b128 v[82:85], v42 offset:192
	s_waitcnt lgkmcnt(0)
	v_mfma_f32_16x16x32_bf16 v[40:43], v[74:77], v[82:85], v[38:41]

; __global__ void __launch_bounds__(NTHR, 2) fwd_megakernel(Args a) {
	.amdhsa_kernel _Z14fwd_megakernel4Args
		.amdhsa_group_segment_fixed_size 0
		.amdhsa_private_segment_fixed_size 0
		.amdhsa_kernarg_size 408
		.amdhsa_user_sgpr_count 2
		.amdhsa_user_sgpr_dispatch_ptr 0
		.amdhsa_user_sgpr_queue_ptr 0
		.amdhsa_user_sgpr_kernarg_segment_ptr 1
		.amdhsa_user_sgpr_dispatch_id 0
		.amdhsa_user_sgpr_kernarg_preload_length 0
		.amdhsa_user_sgpr_kernarg_preload_offset 0
		.amdhsa_user_sgpr_private_segment_size 0
		.amdhsa_uses_dynamic_stack 0
		.amdhsa_enable_private_segment 0
		.amdhsa_system_sgpr_workgroup_id_x 1
		.amdhsa_system_sgpr_workgroup_id_y 0
		.amdhsa_system_sgpr_workgroup_id_z 0
		.amdhsa_system_sgpr_workgroup_info 0
		.amdhsa_system_vgpr_workitem_id 2
		.amdhsa_next_free_vgpr 250
		.amdhsa_next_free_sgpr 102
		.amdhsa_accum_offset 252
		.amdhsa_reserve_vcc 1
		.amdhsa_float_round_mode_32 0
		.amdhsa_float_round_mode_16_64 0
		.amdhsa_float_denorm_mode_32 3
		.amdhsa_float_denorm_mode_16_64 3
		.amdhsa_dx10_clamp 1
		.amdhsa_ieee_mode 1
		.amdhsa_fp16_overflow 0
		.amdhsa_tg_split 0
		.amdhsa_exception_fp_ieee_invalid_op 0
		.amdhsa_exception_fp_denorm_src 0
		.amdhsa_exception_fp_ieee_div_zero 0
		.amdhsa_exception_fp_ieee_overflow 0
		.amdhsa_exception_fp_ieee_underflow 0
		.amdhsa_exception_fp_ieee_inexact 0
		.amdhsa_exception_int_div_zero 0
	.end_amdhsa_kernel

; __global__ void __launch_bounds__(NTHR, 2) fwd_megakernel(Args a) {
amdhsa.kernels:
  - .agpr_count:     0
    .args:
      - .offset:         0
        .size:           152
        .value_kind:     by_value
      - .offset:         152
        .size:           4
        .value_kind:     hidden_block_count_x
      - .offset:         156
        .size:           4
        .value_kind:     hidden_block_count_y
      - .offset:         160
        .size:           4
        .value_kind:     hidden_block_count_z
      - .offset:         164
        .size:           2
        .value_kind:     hidden_group_size_x
      - .offset:         166
        .size:           2
        .value_kind:     hidden_group_size_y
      - .offset:         168
        .size:           2
        .value_kind:     hidden_group_size_z
      - .offset:         170
        .size:           2
        .value_kind:     hidden_remainder_x
      - .offset:         172
        .size:           2
        .value_kind:     hidden_remainder_y
      - .offset:         174
        .size:           2
        .value_kind:     hidden_remainder_z
      - .offset:         192
        .size:           8
        .value_kind:     hidden_global_offset_x
      - .offset:         200
        .size:           8
        .value_kind:     hidden_global_offset_y
      - .offset:         208
        .size:           8
        .value_kind:     hidden_global_offset_z
      - .offset:         216
        .size:           2
        .value_kind:     hidden_grid_dims
      - .offset:         240
        .size:           8
        .value_kind:     hidden_multigrid_sync_arg
      - .offset:         272
        .size:           4
        .value_kind:     hidden_dynamic_lds_size
    .group_segment_fixed_size: 0
    .kernarg_segment_align: 8
    .kernarg_segment_size: 408
    .language:       OpenCL C
    .language_version:
      - 2
      - 0
    .max_flat_workgroup_size: 512
    .name:           _Z14fwd_megakernel4Args
    .private_segment_fixed_size: 0
    .sgpr_count:     108
    .sgpr_spill_count: 200
    .symbol:         _Z14fwd_megakernel4Args.kd
    .uniform_work_group_size: 1
    .uses_dynamic_stack: false
    .vgpr_count:     250
    .vgpr_spill_count: 0
    .wavefront_size: 64
